# strategy: one static priority raise for the younger half (waves 4-7) at kernel start, all per-segment setprio flips deleted
# speedup vs baseline: 1.0040x; 1.0040x over previous
_Z3fwd4Args:
	v_readfirstlane_b32 s98, v0
	s_nop 3
	s_and_b32 s98, s98, 0x3ff
	s_lshr_b32 s98, s98, 6
	s_cmp_ge_u32 s98, 4
	s_cbranch_scc0 .Lprio_done
	s_setprio 1
.Lprio_done:
	s_load_dwordx8 s[84:91], s[0:1], 0x80
	s_load_dword s14, s[0:1], 0xa8
	s_add_u32 s4, s0, 0xa8
	s_addc_u32 s5, s1, 0
	v_and_b32_e32 v66, 0x3ff, v0
	v_writelane_b32 v250, s4, 0
	s_waitcnt lgkmcnt(0)
	s_and_b32 s3, s14, 7
	v_readfirstlane_b32 s52, v66
	v_writelane_b32 v250, s5, 1
	s_mov_b32 s4, s2
	v_writelane_b32 v250, s4, 2
	s_cmp_lg_u32 s3, 0
	s_nop 0
	v_writelane_b32 v250, s5, 3
	v_writelane_b32 v250, s2, 4
	s_cbranch_scc0 .LBB0_66
	s_movk_i32 s2, 0x100
	v_cmp_gt_u32_e64 s[6:7], s2, v66
	s_and_saveexec_b64 s[2:3], s[6:7]

.Lnb_p1:
	s_add_i32 s7, s4, 0xfff84000
	s_cmp_eq_u32 s6, 28
	s_cselect_b32 s17, s0, s7
	s_cselect_b32 s16, s1, s5
	s_or_b32 s7, s17, 0x4000
	s_mov_b32 m0, s79
	s_nop 0
	buffer_load_dwordx4 v242, s[24:27], s4 offen lds
	s_nop 0
	s_mov_b32 m0, s83
	s_nop 0
	buffer_load_dwordx4 v243, s[24:27], s4 offen lds
	s_waitcnt vmcnt(24)
	s_waitcnt lgkmcnt(0)
	s_barrier
	s_waitcnt lgkmcnt(7)
	v_mfma_f32_16x16x32_bf16 v[180:183], v[16:19], v[192:195], 0
	v_mfma_f32_16x16x32_bf16 v[164:167], v[24:27], v[192:195], 0
	s_waitcnt lgkmcnt(5)
	v_mfma_f32_16x16x32_bf16 v[148:151], v[16:19], v[200:203], 0
	v_mfma_f32_16x16x32_bf16 v[140:143], v[24:27], v[200:203], 0
	s_waitcnt lgkmcnt(3)
	v_mfma_f32_16x16x32_bf16 v[132:135], v[16:19], v[220:223], 0
	v_mfma_f32_16x16x32_bf16 v[124:127], v[24:27], v[220:223], 0
	s_waitcnt lgkmcnt(1)
	v_mfma_f32_16x16x32_bf16 v[116:119], v[16:19], v[228:231], 0
	v_mfma_f32_16x16x32_bf16 v[108:111], v[24:27], v[228:231], 0
	v_mfma_f32_16x16x32_bf16 v[180:183], v[20:23], v[196:199], v[180:183]
	v_mfma_f32_16x16x32_bf16 v[164:167], v[28:31], v[196:199], v[164:167]
	v_mfma_f32_16x16x32_bf16 v[148:151], v[20:23], v[204:207], v[148:151]
	v_mfma_f32_16x16x32_bf16 v[140:143], v[28:31], v[204:207], v[140:143]
	v_mfma_f32_16x16x32_bf16 v[132:135], v[20:23], v[224:227], v[132:135]
	v_mfma_f32_16x16x32_bf16 v[124:127], v[28:31], v[224:227], v[124:127]
	s_waitcnt lgkmcnt(0)
	v_mfma_f32_16x16x32_bf16 v[116:119], v[20:23], v[246:249], v[116:119]
	v_mfma_f32_16x16x32_bf16 v[108:111], v[28:31], v[246:249], v[108:111]
	v_mfma_f32_16x16x32_bf16 v[172:175], v[152:155], v[192:195], 0
	v_mfma_f32_16x16x32_bf16 v[156:159], v[168:171], v[192:195], 0
	v_mfma_f32_16x16x32_bf16 v[144:147], v[152:155], v[200:203], 0
	v_mfma_f32_16x16x32_bf16 v[136:139], v[168:171], v[200:203], 0
	v_mfma_f32_16x16x32_bf16 v[128:131], v[152:155], v[220:223], 0
	v_mfma_f32_16x16x32_bf16 v[120:123], v[168:171], v[220:223], 0
	v_mfma_f32_16x16x32_bf16 v[112:115], v[152:155], v[228:231], 0
	v_mfma_f32_16x16x32_bf16 v[104:107], v[168:171], v[228:231], 0
	v_mfma_f32_16x16x32_bf16 v[172:175], v[160:163], v[196:199], v[172:175]
	v_mfma_f32_16x16x32_bf16 v[156:159], v[176:179], v[196:199], v[156:159]
	v_mfma_f32_16x16x32_bf16 v[144:147], v[160:163], v[204:207], v[144:147]
	v_mfma_f32_16x16x32_bf16 v[136:139], v[176:179], v[204:207], v[136:139]
	v_mfma_f32_16x16x32_bf16 v[128:131], v[160:163], v[224:227], v[128:131]
	v_mfma_f32_16x16x32_bf16 v[120:123], v[176:179], v[224:227], v[120:123]
	v_mfma_f32_16x16x32_bf16 v[112:115], v[160:163], v[246:249], v[112:115]
	v_mfma_f32_16x16x32_bf16 v[104:107], v[176:179], v[246:249], v[104:107]
	s_barrier
	ds_read_b128 v[192:195], v245 offset:16384
	ds_read_b128 v[196:199], v245 offset:17408
	ds_read_b128 v[200:203], v245 offset:18432
	ds_read_b128 v[204:207], v245 offset:19456
	ds_read_b128 v[220:223], v245 offset:20480
	ds_read_b128 v[224:227], v245 offset:21504
	ds_read_b128 v[228:231], v245 offset:22528
	ds_read_b128 v[246:249], v245 offset:23552
	s_mov_b32 m0, s51
	s_nop 0
	buffer_load_dwordx4 v242, s[56:59], s16 offen lds
	s_add_i32 s18, s16, 0x80000
	s_mov_b32 m0, s52
	s_nop 0
	buffer_load_dwordx4 v243, s[56:59], s16 offen lds
	s_nop 0
	s_mov_b32 m0, s53
	s_nop 0
	buffer_load_dwordx4 v242, s[56:59], s18 offen lds
	s_nop 0
	s_mov_b32 m0, s55
	s_nop 0
	buffer_load_dwordx4 v243, s[56:59], s18 offen lds
	s_nop 0
	s_mov_b32 m0, s31
	s_nop 0
	buffer_load_dwordx4 v242, s[24:27], s17 offen lds
	s_nop 0
	s_mov_b32 m0, s68
	s_nop 0
	buffer_load_dwordx4 v243, s[24:27], s17 offen lds
	s_waitcnt vmcnt(24)
	s_waitcnt lgkmcnt(0)
	s_barrier
	s_waitcnt lgkmcnt(7)
	v_mfma_f32_16x16x32_bf16 v[76:79], v[16:19], v[192:195], 0
	v_mfma_f32_16x16x32_bf16 v[68:71], v[24:27], v[192:195], 0
	s_waitcnt lgkmcnt(5)
	v_mfma_f32_16x16x32_bf16 v[60:63], v[16:19], v[200:203], 0
	v_mfma_f32_16x16x32_bf16 v[52:55], v[24:27], v[200:203], 0
	s_waitcnt lgkmcnt(3)
	v_mfma_f32_16x16x32_bf16 v[44:47], v[16:19], v[220:223], 0
	v_mfma_f32_16x16x32_bf16 v[36:39], v[24:27], v[220:223], 0
	s_waitcnt lgkmcnt(1)
	v_mfma_f32_16x16x32_bf16 v[12:15], v[16:19], v[228:231], 0
	v_mfma_f32_16x16x32_bf16 v[4:7], v[24:27], v[228:231], 0
	v_mfma_f32_16x16x32_bf16 v[76:79], v[20:23], v[196:199], v[76:79]
	v_mfma_f32_16x16x32_bf16 v[68:71], v[28:31], v[196:199], v[68:71]
	v_mfma_f32_16x16x32_bf16 v[60:63], v[20:23], v[204:207], v[60:63]
	v_mfma_f32_16x16x32_bf16 v[52:55], v[28:31], v[204:207], v[52:55]
	v_mfma_f32_16x16x32_bf16 v[44:47], v[20:23], v[224:227], v[44:47]
	v_mfma_f32_16x16x32_bf16 v[36:39], v[28:31], v[224:227], v[36:39]
	s_waitcnt lgkmcnt(0)
	v_mfma_f32_16x16x32_bf16 v[12:15], v[20:23], v[246:249], v[12:15]
	v_mfma_f32_16x16x32_bf16 v[4:7], v[28:31], v[246:249], v[4:7]
	v_mfma_f32_16x16x32_bf16 v[40:43], v[152:155], v[220:223], 0
	v_mfma_f32_16x16x32_bf16 v[32:35], v[168:171], v[220:223], 0
	v_mfma_f32_16x16x32_bf16 v[8:11], v[152:155], v[228:231], 0
	v_mfma_f32_16x16x32_bf16 v[0:3], v[168:171], v[228:231], 0
	v_mfma_f32_16x16x32_bf16 v[16:19], v[152:155], v[192:195], 0
	v_mfma_f32_16x16x32_bf16 v[20:23], v[168:171], v[192:195], 0
	v_mfma_f32_16x16x32_bf16 v[24:27], v[152:155], v[200:203], 0
	v_mfma_f32_16x16x32_bf16 v[28:31], v[168:171], v[200:203], 0
	v_mfma_f32_16x16x32_bf16 v[40:43], v[160:163], v[224:227], v[40:43]
	v_mfma_f32_16x16x32_bf16 v[32:35], v[176:179], v[224:227], v[32:35]
	v_mfma_f32_16x16x32_bf16 v[8:11], v[160:163], v[246:249], v[8:11]
	v_mfma_f32_16x16x32_bf16 v[0:3], v[176:179], v[246:249], v[0:3]
	v_mfma_f32_16x16x32_bf16 v[16:19], v[160:163], v[196:199], v[16:19]
	v_mfma_f32_16x16x32_bf16 v[20:23], v[176:179], v[196:199], v[20:23]
	v_mfma_f32_16x16x32_bf16 v[24:27], v[160:163], v[204:207], v[24:27]
	v_mfma_f32_16x16x32_bf16 v[28:31], v[176:179], v[204:207], v[28:31]
	s_barrier
	v_add_u32_e32 v72, 0x18000, v83
	v_add_u32_e32 v80, 0x1c000, v83
	ds_read_b128 v[48:51], v72
	ds_read_b128 v[56:59], v72 offset:1024
	ds_read_b128 v[64:67], v72 offset:2048
	ds_read_b128 v[72:75], v72 offset:3072
	ds_read_b128 v[152:155], v80
	ds_read_b128 v[160:163], v80 offset:1024
	ds_read_b128 v[168:171], v80 offset:2048
	ds_read_b128 v[176:179], v80 offset:3072
	ds_read_b128 v[192:195], v245 offset:32768
	ds_read_b128 v[196:199], v245 offset:33792
	ds_read_b128 v[200:203], v245 offset:34816
	ds_read_b128 v[204:207], v245 offset:35840
	ds_read_b128 v[220:223], v245 offset:36864
	ds_read_b128 v[224:227], v245 offset:37888
	ds_read_b128 v[228:231], v245 offset:38912
	ds_read_b128 v[246:249], v245 offset:39936
	s_add_i32 s17, s17, 0x80000
	s_mov_b32 m0, s69
	s_nop 0
	buffer_load_dwordx4 v242, s[24:27], s17 offen lds
	s_nop 0
	s_mov_b32 m0, s70
	s_nop 0
	buffer_load_dwordx4 v243, s[24:27], s17 offen lds
	s_waitcnt vmcnt(8)
	s_waitcnt lgkmcnt(0)
	s_barrier
	s_waitcnt lgkmcnt(7)
	v_mfma_f32_16x16x32_bf16 v[180:183], v[48:51], v[192:195], v[180:183]
	v_mfma_f32_16x16x32_bf16 v[164:167], v[64:67], v[192:195], v[164:167]
	s_waitcnt lgkmcnt(5)
	v_mfma_f32_16x16x32_bf16 v[148:151], v[48:51], v[200:203], v[148:151]
	v_mfma_f32_16x16x32_bf16 v[140:143], v[64:67], v[200:203], v[140:143]
	s_waitcnt lgkmcnt(3)
	v_mfma_f32_16x16x32_bf16 v[132:135], v[48:51], v[220:223], v[132:135]
	v_mfma_f32_16x16x32_bf16 v[124:127], v[64:67], v[220:223], v[124:127]
	s_waitcnt lgkmcnt(1)
	v_mfma_f32_16x16x32_bf16 v[116:119], v[48:51], v[228:231], v[116:119]
	v_mfma_f32_16x16x32_bf16 v[108:111], v[64:67], v[228:231], v[108:111]
	v_mfma_f32_16x16x32_bf16 v[180:183], v[56:59], v[196:199], v[180:183]
	v_mfma_f32_16x16x32_bf16 v[164:167], v[72:75], v[196:199], v[164:167]
	v_mfma_f32_16x16x32_bf16 v[148:151], v[56:59], v[204:207], v[148:151]
	v_mfma_f32_16x16x32_bf16 v[140:143], v[72:75], v[204:207], v[140:143]
	v_mfma_f32_16x16x32_bf16 v[132:135], v[56:59], v[224:227], v[132:135]
	v_mfma_f32_16x16x32_bf16 v[124:127], v[72:75], v[224:227], v[124:127]
	s_waitcnt lgkmcnt(0)
	v_mfma_f32_16x16x32_bf16 v[116:119], v[56:59], v[246:249], v[116:119]
	v_mfma_f32_16x16x32_bf16 v[108:111], v[72:75], v[246:249], v[108:111]
	v_mfma_f32_16x16x32_bf16 v[172:175], v[152:155], v[192:195], v[172:175]
	v_mfma_f32_16x16x32_bf16 v[156:159], v[168:171], v[192:195], v[156:159]
	v_mfma_f32_16x16x32_bf16 v[144:147], v[152:155], v[200:203], v[144:147]
	v_mfma_f32_16x16x32_bf16 v[136:139], v[168:171], v[200:203], v[136:139]
	v_mfma_f32_16x16x32_bf16 v[128:131], v[152:155], v[220:223], v[128:131]
	v_mfma_f32_16x16x32_bf16 v[120:123], v[168:171], v[220:223], v[120:123]
	v_mfma_f32_16x16x32_bf16 v[112:115], v[152:155], v[228:231], v[112:115]
	v_mfma_f32_16x16x32_bf16 v[104:107], v[168:171], v[228:231], v[104:107]
	v_mfma_f32_16x16x32_bf16 v[172:175], v[160:163], v[196:199], v[172:175]
	v_mfma_f32_16x16x32_bf16 v[156:159], v[176:179], v[196:199], v[156:159]
	v_mfma_f32_16x16x32_bf16 v[144:147], v[160:163], v[204:207], v[144:147]
	v_mfma_f32_16x16x32_bf16 v[136:139], v[176:179], v[204:207], v[136:139]
	v_mfma_f32_16x16x32_bf16 v[128:131], v[160:163], v[224:227], v[128:131]
	v_mfma_f32_16x16x32_bf16 v[120:123], v[176:179], v[224:227], v[120:123]
	v_mfma_f32_16x16x32_bf16 v[112:115], v[160:163], v[246:249], v[112:115]
	v_mfma_f32_16x16x32_bf16 v[104:107], v[176:179], v[246:249], v[104:107]
	s_barrier
	ds_read_b128 v[192:195], v245 offset:49152
	ds_read_b128 v[196:199], v245 offset:50176
	ds_read_b128 v[200:203], v245 offset:51200
	ds_read_b128 v[204:207], v245 offset:52224
	ds_read_b128 v[220:223], v245 offset:53248
	ds_read_b128 v[224:227], v245 offset:54272
	ds_read_b128 v[228:231], v245 offset:55296
	ds_read_b128 v[246:249], v245 offset:56320
	s_or_b32 s17, s16, 0x4000
	s_mov_b32 m0, s73
	s_nop 0
	buffer_load_dwordx4 v242, s[56:59], s17 offen lds
	s_add_i32 s16, s16, 0x84000
	s_mov_b32 m0, s74
	s_nop 0
	buffer_load_dwordx4 v243, s[56:59], s17 offen lds
	s_nop 0
	s_mov_b32 m0, s77
	s_nop 0
	buffer_load_dwordx4 v242, s[56:59], s16 offen lds
	s_nop 0
	s_mov_b32 m0, s78
	s_nop 0
	buffer_load_dwordx4 v243, s[56:59], s16 offen lds
	s_nop 0
	s_mov_b32 m0, s75
	s_nop 0
	buffer_load_dwordx4 v242, s[24:27], s7 offen lds
	s_nop 0
	s_mov_b32 m0, s76
	s_nop 0
	buffer_load_dwordx4 v243, s[24:27], s7 offen lds
	s_waitcnt vmcnt(8)
	s_waitcnt lgkmcnt(0)
	s_barrier
	s_waitcnt lgkmcnt(7)
	v_mfma_f32_16x16x32_bf16 v[76:79], v[48:51], v[192:195], v[76:79]
	v_mfma_f32_16x16x32_bf16 v[68:71], v[64:67], v[192:195], v[68:71]
	s_waitcnt lgkmcnt(5)
	v_mfma_f32_16x16x32_bf16 v[60:63], v[48:51], v[200:203], v[60:63]
	v_mfma_f32_16x16x32_bf16 v[52:55], v[64:67], v[200:203], v[52:55]
	s_waitcnt lgkmcnt(3)
	v_mfma_f32_16x16x32_bf16 v[44:47], v[48:51], v[220:223], v[44:47]
	v_mfma_f32_16x16x32_bf16 v[36:39], v[64:67], v[220:223], v[36:39]
	s_waitcnt lgkmcnt(1)
	v_mfma_f32_16x16x32_bf16 v[12:15], v[48:51], v[228:231], v[12:15]
	v_mfma_f32_16x16x32_bf16 v[4:7], v[64:67], v[228:231], v[4:7]
	v_mfma_f32_16x16x32_bf16 v[76:79], v[56:59], v[196:199], v[76:79]
	v_mfma_f32_16x16x32_bf16 v[68:71], v[72:75], v[196:199], v[68:71]
	v_mfma_f32_16x16x32_bf16 v[60:63], v[56:59], v[204:207], v[60:63]
	v_mfma_f32_16x16x32_bf16 v[52:55], v[72:75], v[204:207], v[52:55]
	v_mfma_f32_16x16x32_bf16 v[44:47], v[56:59], v[224:227], v[44:47]
	v_mfma_f32_16x16x32_bf16 v[36:39], v[72:75], v[224:227], v[36:39]
	s_waitcnt lgkmcnt(0)
	v_mfma_f32_16x16x32_bf16 v[12:15], v[56:59], v[246:249], v[12:15]
	v_mfma_f32_16x16x32_bf16 v[4:7], v[72:75], v[246:249], v[4:7]
	v_mfma_f32_16x16x32_bf16 v[16:19], v[152:155], v[192:195], v[16:19]
	v_mfma_f32_16x16x32_bf16 v[72:75], v[160:163], v[196:199], v[16:19]
	v_mfma_f32_16x16x32_bf16 v[16:19], v[168:171], v[192:195], v[20:23]
	v_mfma_f32_16x16x32_bf16 v[64:67], v[176:179], v[196:199], v[16:19]
	v_mfma_f32_16x16x32_bf16 v[16:19], v[152:155], v[200:203], v[24:27]
	v_mfma_f32_16x16x32_bf16 v[56:59], v[160:163], v[204:207], v[16:19]
	v_mfma_f32_16x16x32_bf16 v[16:19], v[168:171], v[200:203], v[28:31]
	v_mfma_f32_16x16x32_bf16 v[48:51], v[176:179], v[204:207], v[16:19]
	v_mfma_f32_16x16x32_bf16 v[16:19], v[152:155], v[220:223], v[40:43]
	v_mfma_f32_16x16x32_bf16 v[40:43], v[160:163], v[224:227], v[16:19]
	v_mfma_f32_16x16x32_bf16 v[16:19], v[168:171], v[220:223], v[32:35]
	v_mfma_f32_16x16x32_bf16 v[8:11], v[152:155], v[228:231], v[8:11]
	v_mfma_f32_16x16x32_bf16 v[0:3], v[168:171], v[228:231], v[0:3]
	v_mfma_f32_16x16x32_bf16 v[32:35], v[176:179], v[224:227], v[16:19]
	v_mfma_f32_16x16x32_bf16 v[8:11], v[160:163], v[246:249], v[8:11]
	v_mfma_f32_16x16x32_bf16 v[0:3], v[176:179], v[246:249], v[0:3]
	s_barrier
	s_add_i32 s6, s6, 2
	s_add_i32 s4, s4, 0x8000
	s_add_i32 s5, s5, 0x8000
.LBB0_143:
	v_add_u32_e32 v28, 0x10000, v83
	v_add_u32_e32 v80, 0x14000, v83
	ds_read_b128 v[16:19], v28
	ds_read_b128 v[20:23], v28 offset:1024
	ds_read_b128 v[24:27], v28 offset:2048
	ds_read_b128 v[28:31], v28 offset:3072
	ds_read_b128 v[152:155], v80
	ds_read_b128 v[160:163], v80 offset:1024
	ds_read_b128 v[168:171], v80 offset:2048
	ds_read_b128 v[176:179], v80 offset:3072
	s_add_i32 s7, s4, 0xfff84000
	s_cmp_eq_u32 s6, 28
	s_cselect_b32 s17, s0, s7
	s_cselect_b32 s16, s1, s5
	s_or_b32 s7, s17, 0x4000
	ds_read_b128 v[192:195], v245
	ds_read_b128 v[196:199], v245 offset:1024
	ds_read_b128 v[200:203], v245 offset:2048
	ds_read_b128 v[204:207], v245 offset:3072
	ds_read_b128 v[220:223], v245 offset:4096
	ds_read_b128 v[224:227], v245 offset:5120
	ds_read_b128 v[228:231], v245 offset:6144
	ds_read_b128 v[246:249], v245 offset:7168
	s_mov_b32 m0, s79
	s_nop 0
	buffer_load_dwordx4 v242, s[24:27], s4 offen lds
	s_nop 0
	s_mov_b32 m0, s83
	s_nop 0
	buffer_load_dwordx4 v243, s[24:27], s4 offen lds
	s_waitcnt vmcnt(8)
	s_waitcnt lgkmcnt(0)
	s_barrier
	s_waitcnt lgkmcnt(7)
	v_mfma_f32_16x16x32_bf16 v[180:183], v[16:19], v[192:195], v[180:183]
	v_mfma_f32_16x16x32_bf16 v[164:167], v[24:27], v[192:195], v[164:167]
	s_waitcnt lgkmcnt(5)
	v_mfma_f32_16x16x32_bf16 v[148:151], v[16:19], v[200:203], v[148:151]
	v_mfma_f32_16x16x32_bf16 v[140:143], v[24:27], v[200:203], v[140:143]
	s_waitcnt lgkmcnt(3)
	v_mfma_f32_16x16x32_bf16 v[132:135], v[16:19], v[220:223], v[132:135]
	v_mfma_f32_16x16x32_bf16 v[124:127], v[24:27], v[220:223], v[124:127]
	s_waitcnt lgkmcnt(1)
	v_mfma_f32_16x16x32_bf16 v[116:119], v[16:19], v[228:231], v[116:119]
	v_mfma_f32_16x16x32_bf16 v[108:111], v[24:27], v[228:231], v[108:111]
	v_mfma_f32_16x16x32_bf16 v[180:183], v[20:23], v[196:199], v[180:183]
	v_mfma_f32_16x16x32_bf16 v[164:167], v[28:31], v[196:199], v[164:167]
	v_mfma_f32_16x16x32_bf16 v[148:151], v[20:23], v[204:207], v[148:151]
	v_mfma_f32_16x16x32_bf16 v[140:143], v[28:31], v[204:207], v[140:143]
	v_mfma_f32_16x16x32_bf16 v[132:135], v[20:23], v[224:227], v[132:135]
	v_mfma_f32_16x16x32_bf16 v[124:127], v[28:31], v[224:227], v[124:127]
	s_waitcnt lgkmcnt(0)
	v_mfma_f32_16x16x32_bf16 v[116:119], v[20:23], v[246:249], v[116:119]
	v_mfma_f32_16x16x32_bf16 v[108:111], v[28:31], v[246:249], v[108:111]
	v_mfma_f32_16x16x32_bf16 v[172:175], v[152:155], v[192:195], v[172:175]
	v_mfma_f32_16x16x32_bf16 v[156:159], v[168:171], v[192:195], v[156:159]
	v_mfma_f32_16x16x32_bf16 v[144:147], v[152:155], v[200:203], v[144:147]
	v_mfma_f32_16x16x32_bf16 v[136:139], v[168:171], v[200:203], v[136:139]
	v_mfma_f32_16x16x32_bf16 v[128:131], v[152:155], v[220:223], v[128:131]
	v_mfma_f32_16x16x32_bf16 v[120:123], v[168:171], v[220:223], v[120:123]
	v_mfma_f32_16x16x32_bf16 v[112:115], v[152:155], v[228:231], v[112:115]
	v_mfma_f32_16x16x32_bf16 v[104:107], v[168:171], v[228:231], v[104:107]
	v_mfma_f32_16x16x32_bf16 v[172:175], v[160:163], v[196:199], v[172:175]
	v_mfma_f32_16x16x32_bf16 v[156:159], v[176:179], v[196:199], v[156:159]
	v_mfma_f32_16x16x32_bf16 v[144:147], v[160:163], v[204:207], v[144:147]
	v_mfma_f32_16x16x32_bf16 v[136:139], v[176:179], v[204:207], v[136:139]
	v_mfma_f32_16x16x32_bf16 v[128:131], v[160:163], v[224:227], v[128:131]
	v_mfma_f32_16x16x32_bf16 v[120:123], v[176:179], v[224:227], v[120:123]
	v_mfma_f32_16x16x32_bf16 v[112:115], v[160:163], v[246:249], v[112:115]
	v_mfma_f32_16x16x32_bf16 v[104:107], v[176:179], v[246:249], v[104:107]
	s_barrier
	ds_read_b128 v[192:195], v245 offset:16384
	ds_read_b128 v[196:199], v245 offset:17408
	ds_read_b128 v[200:203], v245 offset:18432
	ds_read_b128 v[204:207], v245 offset:19456
	ds_read_b128 v[220:223], v245 offset:20480
	ds_read_b128 v[224:227], v245 offset:21504
	ds_read_b128 v[228:231], v245 offset:22528
	ds_read_b128 v[246:249], v245 offset:23552
	s_mov_b32 m0, s51
	s_nop 0
	buffer_load_dwordx4 v242, s[56:59], s16 offen lds
	s_add_i32 s18, s16, 0x80000
	s_mov_b32 m0, s52
	s_nop 0
	buffer_load_dwordx4 v243, s[56:59], s16 offen lds
	s_nop 0
	s_mov_b32 m0, s53
	s_nop 0
	buffer_load_dwordx4 v242, s[56:59], s18 offen lds
	s_nop 0
	s_mov_b32 m0, s55
	s_nop 0
	buffer_load_dwordx4 v243, s[56:59], s18 offen lds
	s_nop 0
	s_mov_b32 m0, s31
	s_nop 0
	buffer_load_dwordx4 v242, s[24:27], s17 offen lds
	s_nop 0
	s_mov_b32 m0, s68
	s_nop 0
	buffer_load_dwordx4 v243, s[24:27], s17 offen lds
	s_waitcnt vmcnt(8)
	s_waitcnt lgkmcnt(0)
	s_barrier
	s_waitcnt lgkmcnt(7)
	v_mfma_f32_16x16x32_bf16 v[76:79], v[16:19], v[192:195], v[76:79]
	v_mfma_f32_16x16x32_bf16 v[68:71], v[24:27], v[192:195], v[68:71]
	s_waitcnt lgkmcnt(5)
	v_mfma_f32_16x16x32_bf16 v[60:63], v[16:19], v[200:203], v[60:63]
	v_mfma_f32_16x16x32_bf16 v[52:55], v[24:27], v[200:203], v[52:55]
	s_waitcnt lgkmcnt(3)
	v_mfma_f32_16x16x32_bf16 v[44:47], v[16:19], v[220:223], v[44:47]
	v_mfma_f32_16x16x32_bf16 v[36:39], v[24:27], v[220:223], v[36:39]
	s_waitcnt lgkmcnt(1)
	v_mfma_f32_16x16x32_bf16 v[12:15], v[16:19], v[228:231], v[12:15]
	v_mfma_f32_16x16x32_bf16 v[4:7], v[24:27], v[228:231], v[4:7]
	v_mfma_f32_16x16x32_bf16 v[76:79], v[20:23], v[196:199], v[76:79]
	v_mfma_f32_16x16x32_bf16 v[68:71], v[28:31], v[196:199], v[68:71]
	v_mfma_f32_16x16x32_bf16 v[60:63], v[20:23], v[204:207], v[60:63]
	v_mfma_f32_16x16x32_bf16 v[52:55], v[28:31], v[204:207], v[52:55]
	v_mfma_f32_16x16x32_bf16 v[44:47], v[20:23], v[224:227], v[44:47]
	v_mfma_f32_16x16x32_bf16 v[36:39], v[28:31], v[224:227], v[36:39]
	s_waitcnt lgkmcnt(0)
	v_mfma_f32_16x16x32_bf16 v[12:15], v[20:23], v[246:249], v[12:15]
	v_mfma_f32_16x16x32_bf16 v[4:7], v[28:31], v[246:249], v[4:7]
	v_mfma_f32_16x16x32_bf16 v[40:43], v[152:155], v[220:223], v[40:43]
	v_mfma_f32_16x16x32_bf16 v[32:35], v[168:171], v[220:223], v[32:35]
	v_mfma_f32_16x16x32_bf16 v[8:11], v[152:155], v[228:231], v[8:11]
	v_mfma_f32_16x16x32_bf16 v[0:3], v[168:171], v[228:231], v[0:3]
	v_mfma_f32_16x16x32_bf16 v[16:19], v[152:155], v[192:195], v[72:75]
	v_mfma_f32_16x16x32_bf16 v[20:23], v[168:171], v[192:195], v[64:67]
	v_mfma_f32_16x16x32_bf16 v[24:27], v[152:155], v[200:203], v[56:59]
	v_mfma_f32_16x16x32_bf16 v[28:31], v[168:171], v[200:203], v[48:51]
	v_mfma_f32_16x16x32_bf16 v[40:43], v[160:163], v[224:227], v[40:43]
	v_mfma_f32_16x16x32_bf16 v[32:35], v[176:179], v[224:227], v[32:35]
	v_mfma_f32_16x16x32_bf16 v[8:11], v[160:163], v[246:249], v[8:11]
	v_mfma_f32_16x16x32_bf16 v[0:3], v[176:179], v[246:249], v[0:3]
	v_mfma_f32_16x16x32_bf16 v[16:19], v[160:163], v[196:199], v[16:19]
	v_mfma_f32_16x16x32_bf16 v[20:23], v[176:179], v[196:199], v[20:23]
	v_mfma_f32_16x16x32_bf16 v[24:27], v[160:163], v[204:207], v[24:27]
	v_mfma_f32_16x16x32_bf16 v[28:31], v[176:179], v[204:207], v[28:31]
	s_barrier
	v_add_u32_e32 v72, 0x18000, v83
	v_add_u32_e32 v80, 0x1c000, v83
	ds_read_b128 v[48:51], v72
	ds_read_b128 v[56:59], v72 offset:1024
	ds_read_b128 v[64:67], v72 offset:2048
	ds_read_b128 v[72:75], v72 offset:3072
	ds_read_b128 v[152:155], v80
	ds_read_b128 v[160:163], v80 offset:1024
	ds_read_b128 v[168:171], v80 offset:2048
	ds_read_b128 v[176:179], v80 offset:3072
	ds_read_b128 v[192:195], v245 offset:32768
	ds_read_b128 v[196:199], v245 offset:33792
	ds_read_b128 v[200:203], v245 offset:34816
	ds_read_b128 v[204:207], v245 offset:35840
	ds_read_b128 v[220:223], v245 offset:36864
	ds_read_b128 v[224:227], v245 offset:37888
	ds_read_b128 v[228:231], v245 offset:38912
	ds_read_b128 v[246:249], v245 offset:39936
	s_add_i32 s17, s17, 0x80000
	s_mov_b32 m0, s69
	s_nop 0
	buffer_load_dwordx4 v242, s[24:27], s17 offen lds
	s_nop 0
	s_mov_b32 m0, s70
	s_nop 0
	buffer_load_dwordx4 v243, s[24:27], s17 offen lds
	s_waitcnt vmcnt(8)
	s_waitcnt lgkmcnt(0)
	s_barrier
	s_waitcnt lgkmcnt(7)
	v_mfma_f32_16x16x32_bf16 v[180:183], v[48:51], v[192:195], v[180:183]
	v_mfma_f32_16x16x32_bf16 v[164:167], v[64:67], v[192:195], v[164:167]
	s_waitcnt lgkmcnt(5)
	v_mfma_f32_16x16x32_bf16 v[148:151], v[48:51], v[200:203], v[148:151]
	v_mfma_f32_16x16x32_bf16 v[140:143], v[64:67], v[200:203], v[140:143]
	s_waitcnt lgkmcnt(3)
	v_mfma_f32_16x16x32_bf16 v[132:135], v[48:51], v[220:223], v[132:135]
	v_mfma_f32_16x16x32_bf16 v[124:127], v[64:67], v[220:223], v[124:127]
	s_waitcnt lgkmcnt(1)
	v_mfma_f32_16x16x32_bf16 v[116:119], v[48:51], v[228:231], v[116:119]
	v_mfma_f32_16x16x32_bf16 v[108:111], v[64:67], v[228:231], v[108:111]
	v_mfma_f32_16x16x32_bf16 v[180:183], v[56:59], v[196:199], v[180:183]
	v_mfma_f32_16x16x32_bf16 v[164:167], v[72:75], v[196:199], v[164:167]
	v_mfma_f32_16x16x32_bf16 v[148:151], v[56:59], v[204:207], v[148:151]
	v_mfma_f32_16x16x32_bf16 v[140:143], v[72:75], v[204:207], v[140:143]
	v_mfma_f32_16x16x32_bf16 v[132:135], v[56:59], v[224:227], v[132:135]
	v_mfma_f32_16x16x32_bf16 v[124:127], v[72:75], v[224:227], v[124:127]
	s_waitcnt lgkmcnt(0)
	v_mfma_f32_16x16x32_bf16 v[116:119], v[56:59], v[246:249], v[116:119]
	v_mfma_f32_16x16x32_bf16 v[108:111], v[72:75], v[246:249], v[108:111]
	v_mfma_f32_16x16x32_bf16 v[172:175], v[152:155], v[192:195], v[172:175]
	v_mfma_f32_16x16x32_bf16 v[156:159], v[168:171], v[192:195], v[156:159]
	v_mfma_f32_16x16x32_bf16 v[144:147], v[152:155], v[200:203], v[144:147]
	v_mfma_f32_16x16x32_bf16 v[136:139], v[168:171], v[200:203], v[136:139]
	v_mfma_f32_16x16x32_bf16 v[128:131], v[152:155], v[220:223], v[128:131]
	v_mfma_f32_16x16x32_bf16 v[120:123], v[168:171], v[220:223], v[120:123]
	v_mfma_f32_16x16x32_bf16 v[112:115], v[152:155], v[228:231], v[112:115]
	v_mfma_f32_16x16x32_bf16 v[104:107], v[168:171], v[228:231], v[104:107]
	v_mfma_f32_16x16x32_bf16 v[172:175], v[160:163], v[196:199], v[172:175]
	v_mfma_f32_16x16x32_bf16 v[156:159], v[176:179], v[196:199], v[156:159]
	v_mfma_f32_16x16x32_bf16 v[144:147], v[160:163], v[204:207], v[144:147]
	v_mfma_f32_16x16x32_bf16 v[136:139], v[176:179], v[204:207], v[136:139]
	v_mfma_f32_16x16x32_bf16 v[128:131], v[160:163], v[224:227], v[128:131]
	v_mfma_f32_16x16x32_bf16 v[120:123], v[176:179], v[224:227], v[120:123]
	v_mfma_f32_16x16x32_bf16 v[112:115], v[160:163], v[246:249], v[112:115]
	v_mfma_f32_16x16x32_bf16 v[104:107], v[176:179], v[246:249], v[104:107]
	s_barrier
	ds_read_b128 v[192:195], v245 offset:49152
	ds_read_b128 v[196:199], v245 offset:50176
	ds_read_b128 v[200:203], v245 offset:51200
	ds_read_b128 v[204:207], v245 offset:52224
	ds_read_b128 v[220:223], v245 offset:53248
	ds_read_b128 v[224:227], v245 offset:54272
	ds_read_b128 v[228:231], v245 offset:55296
	ds_read_b128 v[246:249], v245 offset:56320
	s_or_b32 s17, s16, 0x4000
	s_mov_b32 m0, s73
	s_nop 0
	buffer_load_dwordx4 v242, s[56:59], s17 offen lds
	s_add_i32 s16, s16, 0x84000
	s_mov_b32 m0, s74
	s_nop 0
	buffer_load_dwordx4 v243, s[56:59], s17 offen lds
	s_nop 0
	s_mov_b32 m0, s77
	s_nop 0
	buffer_load_dwordx4 v242, s[56:59], s16 offen lds
	s_nop 0
	s_mov_b32 m0, s78
	s_nop 0
	buffer_load_dwordx4 v243, s[56:59], s16 offen lds
	s_nop 0
	s_mov_b32 m0, s75
	s_nop 0
	buffer_load_dwordx4 v242, s[24:27], s7 offen lds
	s_nop 0
	s_mov_b32 m0, s76
	s_nop 0
	buffer_load_dwordx4 v243, s[24:27], s7 offen lds
	s_waitcnt vmcnt(8)
	s_waitcnt lgkmcnt(0)
	s_barrier
	s_waitcnt lgkmcnt(7)
	v_mfma_f32_16x16x32_bf16 v[76:79], v[48:51], v[192:195], v[76:79]
	v_mfma_f32_16x16x32_bf16 v[68:71], v[64:67], v[192:195], v[68:71]
	s_waitcnt lgkmcnt(5)
	v_mfma_f32_16x16x32_bf16 v[60:63], v[48:51], v[200:203], v[60:63]
	v_mfma_f32_16x16x32_bf16 v[52:55], v[64:67], v[200:203], v[52:55]
	s_waitcnt lgkmcnt(3)
	v_mfma_f32_16x16x32_bf16 v[44:47], v[48:51], v[220:223], v[44:47]
	v_mfma_f32_16x16x32_bf16 v[36:39], v[64:67], v[220:223], v[36:39]
	s_waitcnt lgkmcnt(1)
	v_mfma_f32_16x16x32_bf16 v[12:15], v[48:51], v[228:231], v[12:15]
	v_mfma_f32_16x16x32_bf16 v[4:7], v[64:67], v[228:231], v[4:7]
	v_mfma_f32_16x16x32_bf16 v[76:79], v[56:59], v[196:199], v[76:79]
	v_mfma_f32_16x16x32_bf16 v[68:71], v[72:75], v[196:199], v[68:71]
	v_mfma_f32_16x16x32_bf16 v[60:63], v[56:59], v[204:207], v[60:63]
	v_mfma_f32_16x16x32_bf16 v[52:55], v[72:75], v[204:207], v[52:55]
	v_mfma_f32_16x16x32_bf16 v[44:47], v[56:59], v[224:227], v[44:47]
	v_mfma_f32_16x16x32_bf16 v[36:39], v[72:75], v[224:227], v[36:39]
	s_waitcnt lgkmcnt(0)
	v_mfma_f32_16x16x32_bf16 v[12:15], v[56:59], v[246:249], v[12:15]
	v_mfma_f32_16x16x32_bf16 v[4:7], v[72:75], v[246:249], v[4:7]
	v_mfma_f32_16x16x32_bf16 v[16:19], v[152:155], v[192:195], v[16:19]
	v_mfma_f32_16x16x32_bf16 v[72:75], v[160:163], v[196:199], v[16:19]
	v_mfma_f32_16x16x32_bf16 v[16:19], v[168:171], v[192:195], v[20:23]
	v_mfma_f32_16x16x32_bf16 v[64:67], v[176:179], v[196:199], v[16:19]
	v_mfma_f32_16x16x32_bf16 v[16:19], v[152:155], v[200:203], v[24:27]
	v_mfma_f32_16x16x32_bf16 v[56:59], v[160:163], v[204:207], v[16:19]
	v_mfma_f32_16x16x32_bf16 v[16:19], v[168:171], v[200:203], v[28:31]
	v_mfma_f32_16x16x32_bf16 v[48:51], v[176:179], v[204:207], v[16:19]
	v_mfma_f32_16x16x32_bf16 v[16:19], v[152:155], v[220:223], v[40:43]
	v_mfma_f32_16x16x32_bf16 v[40:43], v[160:163], v[224:227], v[16:19]
	v_mfma_f32_16x16x32_bf16 v[16:19], v[168:171], v[220:223], v[32:35]
	v_mfma_f32_16x16x32_bf16 v[8:11], v[152:155], v[228:231], v[8:11]
	v_mfma_f32_16x16x32_bf16 v[0:3], v[168:171], v[228:231], v[0:3]
	v_mfma_f32_16x16x32_bf16 v[32:35], v[176:179], v[224:227], v[16:19]
	v_mfma_f32_16x16x32_bf16 v[8:11], v[160:163], v[246:249], v[8:11]
	v_mfma_f32_16x16x32_bf16 v[0:3], v[176:179], v[246:249], v[0:3]
	s_barrier
	s_add_i32 s6, s6, 2
	s_add_i32 s4, s4, 0x8000
	s_add_i32 s5, s5, 0x8000
	s_cmp_gt_u32 s6, 29
	s_cbranch_scc0 .LBB0_143

.LBB0_594:
	v_add_u32_e32 v80, 0x10000, v226
	ds_read_b128 v[152:155], v80
	ds_read_b128 v[156:159], v80 offset:1024
	ds_read_b128 v[160:163], v80 offset:2048
	ds_read_b128 v[164:167], v80 offset:3072
	v_add_u32_e32 v80, 0x14000, v226
	ds_read_b128 v[168:171], v80
	ds_read_b128 v[172:175], v80 offset:1024
	ds_read_b128 v[176:179], v80 offset:2048
	ds_read_b128 v[180:183], v80 offset:3072
	s_add_i32 s97, s96, s39
	s_add_i32 s94, s97, 0x8000
	s_add_i32 s95, s93, s39
	s_cmp_eq_u32 s39, 0x78000
	s_cselect_b32 s36, vcc_lo, s94
	s_cselect_b32 s95, vcc_hi, s95
	s_or_b32 s94, s36, 0x4000
	ds_read_b128 v[184:187], v227
	ds_read_b128 v[188:191], v227 offset:1024
	ds_read_b128 v[192:195], v227 offset:2048
	ds_read_b128 v[196:199], v227 offset:3072
	ds_read_b128 v[200:203], v227 offset:4096
	ds_read_b128 v[204:207], v227 offset:5120
	ds_read_b128 v[228:231], v227 offset:6144
	ds_read_b128 v[240:243], v227 offset:7168
	s_add_i32 s97, s97, 0x84000
	s_mov_b32 m0, s85
	s_nop 0
	buffer_load_dwordx4 v224, s[60:63], s97 offen lds
	s_nop 0
	s_mov_b32 m0, s86
	s_nop 0
	buffer_load_dwordx4 v225, s[60:63], s97 offen lds
	s_waitcnt vmcnt(8)
	s_waitcnt lgkmcnt(0)
	s_barrier
	s_waitcnt lgkmcnt(7)
	v_mfma_f32_16x16x32_bf16 v[148:151], v[152:155], v[184:187], v[148:151]
	v_mfma_f32_16x16x32_bf16 v[144:147], v[160:163], v[184:187], v[144:147]
	s_waitcnt lgkmcnt(5)
	v_mfma_f32_16x16x32_bf16 v[132:135], v[152:155], v[192:195], v[132:135]
	v_mfma_f32_16x16x32_bf16 v[128:131], v[160:163], v[192:195], v[128:131]
	s_waitcnt lgkmcnt(3)
	v_mfma_f32_16x16x32_bf16 v[116:119], v[152:155], v[200:203], v[116:119]
	v_mfma_f32_16x16x32_bf16 v[112:115], v[160:163], v[200:203], v[112:115]
	s_waitcnt lgkmcnt(1)
	v_mfma_f32_16x16x32_bf16 v[76:79], v[152:155], v[228:231], v[76:79]
	v_mfma_f32_16x16x32_bf16 v[72:75], v[160:163], v[228:231], v[72:75]
	v_mfma_f32_16x16x32_bf16 v[148:151], v[156:159], v[188:191], v[148:151]
	v_mfma_f32_16x16x32_bf16 v[144:147], v[164:167], v[188:191], v[144:147]
	v_mfma_f32_16x16x32_bf16 v[132:135], v[156:159], v[196:199], v[132:135]
	v_mfma_f32_16x16x32_bf16 v[128:131], v[164:167], v[196:199], v[128:131]
	v_mfma_f32_16x16x32_bf16 v[116:119], v[156:159], v[204:207], v[116:119]
	v_mfma_f32_16x16x32_bf16 v[112:115], v[164:167], v[204:207], v[112:115]
	s_waitcnt lgkmcnt(0)
	v_mfma_f32_16x16x32_bf16 v[76:79], v[156:159], v[240:243], v[76:79]
	v_mfma_f32_16x16x32_bf16 v[72:75], v[164:167], v[240:243], v[72:75]
	v_mfma_f32_16x16x32_bf16 v[140:143], v[168:171], v[184:187], v[140:143]
	v_mfma_f32_16x16x32_bf16 v[136:139], v[176:179], v[184:187], v[136:139]
	v_mfma_f32_16x16x32_bf16 v[124:127], v[168:171], v[192:195], v[124:127]
	v_mfma_f32_16x16x32_bf16 v[120:123], v[176:179], v[192:195], v[120:123]
	v_mfma_f32_16x16x32_bf16 v[108:111], v[168:171], v[200:203], v[108:111]
	v_mfma_f32_16x16x32_bf16 v[104:107], v[176:179], v[200:203], v[104:107]
	v_mfma_f32_16x16x32_bf16 v[68:71], v[168:171], v[228:231], v[68:71]
	v_mfma_f32_16x16x32_bf16 v[64:67], v[176:179], v[228:231], v[64:67]
	v_mfma_f32_16x16x32_bf16 v[140:143], v[172:175], v[188:191], v[140:143]
	v_mfma_f32_16x16x32_bf16 v[136:139], v[180:183], v[188:191], v[136:139]
	v_mfma_f32_16x16x32_bf16 v[124:127], v[172:175], v[196:199], v[124:127]
	v_mfma_f32_16x16x32_bf16 v[120:123], v[180:183], v[196:199], v[120:123]
	v_mfma_f32_16x16x32_bf16 v[108:111], v[172:175], v[204:207], v[108:111]
	v_mfma_f32_16x16x32_bf16 v[104:107], v[180:183], v[204:207], v[104:107]
	v_mfma_f32_16x16x32_bf16 v[68:71], v[172:175], v[240:243], v[68:71]
	v_mfma_f32_16x16x32_bf16 v[64:67], v[180:183], v[240:243], v[64:67]
	s_barrier
	ds_read_b128 v[184:187], v227 offset:16384
	ds_read_b128 v[188:191], v227 offset:17408
	ds_read_b128 v[192:195], v227 offset:18432
	ds_read_b128 v[196:199], v227 offset:19456
	ds_read_b128 v[200:203], v227 offset:20480
	ds_read_b128 v[204:207], v227 offset:21504
	ds_read_b128 v[228:231], v227 offset:22528
	ds_read_b128 v[240:243], v227 offset:23552
	s_mov_b32 m0, s34
	s_nop 0
	buffer_load_dwordx4 v224, s[48:51], s95 offen lds
	s_add_i32 s97, s95, 0x80000
	s_mov_b32 m0, s55
	s_nop 0
	buffer_load_dwordx4 v225, s[48:51], s95 offen lds
	s_nop 0
	s_mov_b32 m0, s72
	s_nop 0
	buffer_load_dwordx4 v224, s[48:51], s97 offen lds
	s_nop 0
	s_mov_b32 m0, s73
	s_nop 0
	buffer_load_dwordx4 v225, s[48:51], s97 offen lds
	s_nop 0
	s_mov_b32 m0, s31
	s_nop 0
	buffer_load_dwordx4 v224, s[60:63], s36 offen lds
	s_nop 0
	s_mov_b32 m0, s74
	s_nop 0
	buffer_load_dwordx4 v225, s[60:63], s36 offen lds
	s_waitcnt vmcnt(8)
	s_waitcnt lgkmcnt(0)
	s_barrier
	s_waitcnt lgkmcnt(7)
	v_mfma_f32_16x16x32_bf16 v[60:63], v[152:155], v[184:187], v[60:63]
	v_mfma_f32_16x16x32_bf16 v[56:59], v[160:163], v[184:187], v[56:59]
	s_waitcnt lgkmcnt(5)
	v_mfma_f32_16x16x32_bf16 v[44:47], v[152:155], v[192:195], v[44:47]
	v_mfma_f32_16x16x32_bf16 v[40:43], v[160:163], v[192:195], v[40:43]
	s_waitcnt lgkmcnt(3)
	v_mfma_f32_16x16x32_bf16 v[28:31], v[152:155], v[200:203], v[28:31]
	v_mfma_f32_16x16x32_bf16 v[24:27], v[160:163], v[200:203], v[24:27]
	s_waitcnt lgkmcnt(1)
	v_mfma_f32_16x16x32_bf16 v[12:15], v[152:155], v[228:231], v[12:15]
	v_mfma_f32_16x16x32_bf16 v[8:11], v[160:163], v[228:231], v[8:11]
	v_mfma_f32_16x16x32_bf16 v[60:63], v[156:159], v[188:191], v[60:63]
	v_mfma_f32_16x16x32_bf16 v[56:59], v[164:167], v[188:191], v[56:59]
	v_mfma_f32_16x16x32_bf16 v[44:47], v[156:159], v[196:199], v[44:47]
	v_mfma_f32_16x16x32_bf16 v[40:43], v[164:167], v[196:199], v[40:43]
	v_mfma_f32_16x16x32_bf16 v[28:31], v[156:159], v[204:207], v[28:31]
	v_mfma_f32_16x16x32_bf16 v[24:27], v[164:167], v[204:207], v[24:27]
	s_waitcnt lgkmcnt(0)
	v_mfma_f32_16x16x32_bf16 v[12:15], v[156:159], v[240:243], v[12:15]
	v_mfma_f32_16x16x32_bf16 v[8:11], v[164:167], v[240:243], v[8:11]
	v_mfma_f32_16x16x32_bf16 v[52:55], v[168:171], v[184:187], v[52:55]
	v_mfma_f32_16x16x32_bf16 v[48:51], v[176:179], v[184:187], v[48:51]
	v_mfma_f32_16x16x32_bf16 v[36:39], v[168:171], v[192:195], v[36:39]
	v_mfma_f32_16x16x32_bf16 v[32:35], v[176:179], v[192:195], v[32:35]
	v_mfma_f32_16x16x32_bf16 v[20:23], v[168:171], v[200:203], v[20:23]
	v_mfma_f32_16x16x32_bf16 v[16:19], v[176:179], v[200:203], v[16:19]
	v_mfma_f32_16x16x32_bf16 v[4:7], v[168:171], v[228:231], v[4:7]
	v_mfma_f32_16x16x32_bf16 v[0:3], v[176:179], v[228:231], v[0:3]
	v_mfma_f32_16x16x32_bf16 v[52:55], v[172:175], v[188:191], v[52:55]
	v_mfma_f32_16x16x32_bf16 v[48:51], v[180:183], v[188:191], v[48:51]
	v_mfma_f32_16x16x32_bf16 v[36:39], v[172:175], v[196:199], v[36:39]
	v_mfma_f32_16x16x32_bf16 v[32:35], v[180:183], v[196:199], v[32:35]
	v_mfma_f32_16x16x32_bf16 v[20:23], v[172:175], v[204:207], v[20:23]
	v_mfma_f32_16x16x32_bf16 v[16:19], v[180:183], v[204:207], v[16:19]
	v_mfma_f32_16x16x32_bf16 v[4:7], v[172:175], v[240:243], v[4:7]
	v_mfma_f32_16x16x32_bf16 v[0:3], v[180:183], v[240:243], v[0:3]
	s_barrier
	v_add_u32_e32 v80, 0x18000, v226
	ds_read_b128 v[152:155], v80
	ds_read_b128 v[156:159], v80 offset:1024
	ds_read_b128 v[160:163], v80 offset:2048
	ds_read_b128 v[164:167], v80 offset:3072
	v_add_u32_e32 v80, 0x1c000, v226
	ds_read_b128 v[168:171], v80
	ds_read_b128 v[172:175], v80 offset:1024
	ds_read_b128 v[176:179], v80 offset:2048
	ds_read_b128 v[180:183], v80 offset:3072
	ds_read_b128 v[184:187], v227 offset:32768
	ds_read_b128 v[188:191], v227 offset:33792
	ds_read_b128 v[192:195], v227 offset:34816
	ds_read_b128 v[196:199], v227 offset:35840
	ds_read_b128 v[200:203], v227 offset:36864
	ds_read_b128 v[204:207], v227 offset:37888
	ds_read_b128 v[228:231], v227 offset:38912
	ds_read_b128 v[240:243], v227 offset:39936
	s_add_i32 s36, s36, 0x80000
	s_mov_b32 m0, s75
	s_nop 0
	buffer_load_dwordx4 v224, s[60:63], s36 offen lds
	s_nop 0
	s_mov_b32 m0, s76
	s_nop 0
	buffer_load_dwordx4 v225, s[60:63], s36 offen lds
	s_waitcnt vmcnt(8)
	s_waitcnt lgkmcnt(0)
	s_barrier
	s_waitcnt lgkmcnt(7)
	v_mfma_f32_16x16x32_bf16 v[148:151], v[152:155], v[184:187], v[148:151]
	v_mfma_f32_16x16x32_bf16 v[144:147], v[160:163], v[184:187], v[144:147]
	s_waitcnt lgkmcnt(5)
	v_mfma_f32_16x16x32_bf16 v[132:135], v[152:155], v[192:195], v[132:135]
	v_mfma_f32_16x16x32_bf16 v[128:131], v[160:163], v[192:195], v[128:131]
	s_waitcnt lgkmcnt(3)
	v_mfma_f32_16x16x32_bf16 v[116:119], v[152:155], v[200:203], v[116:119]
	v_mfma_f32_16x16x32_bf16 v[112:115], v[160:163], v[200:203], v[112:115]
	s_waitcnt lgkmcnt(1)
	v_mfma_f32_16x16x32_bf16 v[76:79], v[152:155], v[228:231], v[76:79]
	v_mfma_f32_16x16x32_bf16 v[72:75], v[160:163], v[228:231], v[72:75]
	v_mfma_f32_16x16x32_bf16 v[148:151], v[156:159], v[188:191], v[148:151]
	v_mfma_f32_16x16x32_bf16 v[144:147], v[164:167], v[188:191], v[144:147]
	v_mfma_f32_16x16x32_bf16 v[132:135], v[156:159], v[196:199], v[132:135]
	v_mfma_f32_16x16x32_bf16 v[128:131], v[164:167], v[196:199], v[128:131]
	v_mfma_f32_16x16x32_bf16 v[116:119], v[156:159], v[204:207], v[116:119]
	v_mfma_f32_16x16x32_bf16 v[112:115], v[164:167], v[204:207], v[112:115]
	s_waitcnt lgkmcnt(0)
	v_mfma_f32_16x16x32_bf16 v[76:79], v[156:159], v[240:243], v[76:79]
	v_mfma_f32_16x16x32_bf16 v[72:75], v[164:167], v[240:243], v[72:75]
	v_mfma_f32_16x16x32_bf16 v[140:143], v[168:171], v[184:187], v[140:143]
	v_mfma_f32_16x16x32_bf16 v[136:139], v[176:179], v[184:187], v[136:139]
	v_mfma_f32_16x16x32_bf16 v[124:127], v[168:171], v[192:195], v[124:127]
	v_mfma_f32_16x16x32_bf16 v[120:123], v[176:179], v[192:195], v[120:123]
	v_mfma_f32_16x16x32_bf16 v[108:111], v[168:171], v[200:203], v[108:111]
	v_mfma_f32_16x16x32_bf16 v[104:107], v[176:179], v[200:203], v[104:107]
	v_mfma_f32_16x16x32_bf16 v[68:71], v[168:171], v[228:231], v[68:71]
	v_mfma_f32_16x16x32_bf16 v[64:67], v[176:179], v[228:231], v[64:67]
	v_mfma_f32_16x16x32_bf16 v[140:143], v[172:175], v[188:191], v[140:143]
	v_mfma_f32_16x16x32_bf16 v[136:139], v[180:183], v[188:191], v[136:139]
	v_mfma_f32_16x16x32_bf16 v[124:127], v[172:175], v[196:199], v[124:127]
	v_mfma_f32_16x16x32_bf16 v[120:123], v[180:183], v[196:199], v[120:123]
	v_mfma_f32_16x16x32_bf16 v[108:111], v[172:175], v[204:207], v[108:111]
	v_mfma_f32_16x16x32_bf16 v[104:107], v[180:183], v[204:207], v[104:107]
	v_mfma_f32_16x16x32_bf16 v[68:71], v[172:175], v[240:243], v[68:71]
	v_mfma_f32_16x16x32_bf16 v[64:67], v[180:183], v[240:243], v[64:67]
	s_barrier
	ds_read_b128 v[184:187], v227 offset:49152
	ds_read_b128 v[188:191], v227 offset:50176
	ds_read_b128 v[192:195], v227 offset:51200
	ds_read_b128 v[196:199], v227 offset:52224
	ds_read_b128 v[200:203], v227 offset:53248
	ds_read_b128 v[204:207], v227 offset:54272
	ds_read_b128 v[228:231], v227 offset:55296
	ds_read_b128 v[240:243], v227 offset:56320
	s_or_b32 s36, s95, 0x4000
	s_mov_b32 m0, s77
	s_nop 0
	buffer_load_dwordx4 v224, s[48:51], s36 offen lds
	s_nop 0
	s_mov_b32 m0, s78
	s_nop 0
	buffer_load_dwordx4 v225, s[48:51], s36 offen lds
	s_add_i32 s36, s95, 0x84000
	s_mov_b32 m0, s83
	s_nop 0
	buffer_load_dwordx4 v224, s[48:51], s36 offen lds
	s_nop 0
	s_mov_b32 m0, s84
	s_nop 0
	buffer_load_dwordx4 v225, s[48:51], s36 offen lds
	s_nop 0
	s_mov_b32 m0, s79
	s_nop 0
	buffer_load_dwordx4 v224, s[60:63], s94 offen lds
	s_nop 0
	s_mov_b32 m0, s82
	s_nop 0
	buffer_load_dwordx4 v225, s[60:63], s94 offen lds
	s_waitcnt vmcnt(8)
	s_waitcnt lgkmcnt(0)
	s_barrier
	s_waitcnt lgkmcnt(7)
	v_mfma_f32_16x16x32_bf16 v[60:63], v[152:155], v[184:187], v[60:63]
	v_mfma_f32_16x16x32_bf16 v[56:59], v[160:163], v[184:187], v[56:59]
	s_waitcnt lgkmcnt(5)
	v_mfma_f32_16x16x32_bf16 v[44:47], v[152:155], v[192:195], v[44:47]
	v_mfma_f32_16x16x32_bf16 v[40:43], v[160:163], v[192:195], v[40:43]
	s_waitcnt lgkmcnt(3)
	v_mfma_f32_16x16x32_bf16 v[28:31], v[152:155], v[200:203], v[28:31]
	v_mfma_f32_16x16x32_bf16 v[24:27], v[160:163], v[200:203], v[24:27]
	s_waitcnt lgkmcnt(1)
	v_mfma_f32_16x16x32_bf16 v[12:15], v[152:155], v[228:231], v[12:15]
	v_mfma_f32_16x16x32_bf16 v[8:11], v[160:163], v[228:231], v[8:11]
	v_mfma_f32_16x16x32_bf16 v[60:63], v[156:159], v[188:191], v[60:63]
	v_mfma_f32_16x16x32_bf16 v[56:59], v[164:167], v[188:191], v[56:59]
	v_mfma_f32_16x16x32_bf16 v[44:47], v[156:159], v[196:199], v[44:47]
	v_mfma_f32_16x16x32_bf16 v[40:43], v[164:167], v[196:199], v[40:43]
	v_mfma_f32_16x16x32_bf16 v[28:31], v[156:159], v[204:207], v[28:31]
	v_mfma_f32_16x16x32_bf16 v[24:27], v[164:167], v[204:207], v[24:27]
	s_waitcnt lgkmcnt(0)
	v_mfma_f32_16x16x32_bf16 v[12:15], v[156:159], v[240:243], v[12:15]
	v_mfma_f32_16x16x32_bf16 v[8:11], v[164:167], v[240:243], v[8:11]
	v_mfma_f32_16x16x32_bf16 v[52:55], v[168:171], v[184:187], v[52:55]
	v_mfma_f32_16x16x32_bf16 v[48:51], v[176:179], v[184:187], v[48:51]
	v_mfma_f32_16x16x32_bf16 v[36:39], v[168:171], v[192:195], v[36:39]
	v_mfma_f32_16x16x32_bf16 v[32:35], v[176:179], v[192:195], v[32:35]
	v_mfma_f32_16x16x32_bf16 v[20:23], v[168:171], v[200:203], v[20:23]
	v_mfma_f32_16x16x32_bf16 v[16:19], v[176:179], v[200:203], v[16:19]
	v_mfma_f32_16x16x32_bf16 v[4:7], v[168:171], v[228:231], v[4:7]
	v_mfma_f32_16x16x32_bf16 v[0:3], v[176:179], v[228:231], v[0:3]
	v_mfma_f32_16x16x32_bf16 v[52:55], v[172:175], v[188:191], v[52:55]
	v_mfma_f32_16x16x32_bf16 v[48:51], v[180:183], v[188:191], v[48:51]
	v_mfma_f32_16x16x32_bf16 v[36:39], v[172:175], v[196:199], v[36:39]
	v_mfma_f32_16x16x32_bf16 v[32:35], v[180:183], v[196:199], v[32:35]
	v_mfma_f32_16x16x32_bf16 v[20:23], v[172:175], v[204:207], v[20:23]
	v_mfma_f32_16x16x32_bf16 v[16:19], v[180:183], v[204:207], v[16:19]
	v_mfma_f32_16x16x32_bf16 v[4:7], v[172:175], v[240:243], v[4:7]
	v_mfma_f32_16x16x32_bf16 v[0:3], v[180:183], v[240:243], v[0:3]
	s_barrier
	s_add_i32 s38, s38, 2
	s_add_i32 s39, s39, 0x8000
	s_cmp_gt_u32 s38, 29
	s_cbranch_scc1 .LBB0_597

.Lnb_p4:
	s_add_i32 s11, s8, 0xfff84000
	s_cmp_eq_u32 s10, 28
	s_cselect_b32 s13, s6, s11
	s_cselect_b32 s12, s7, s9
	s_or_b32 s11, s13, 0x4000
	s_mov_b32 m0, s89
	s_nop 0
	buffer_load_dwordx4 v220, s[64:67], s8 offen lds
	s_nop 0
	s_mov_b32 m0, s91
	s_nop 0
	buffer_load_dwordx4 v221, s[64:67], s8 offen lds
	s_waitcnt vmcnt(24)
	s_waitcnt lgkmcnt(0)
	s_barrier
	s_waitcnt lgkmcnt(7)
	v_mfma_f32_16x16x32_bf16 v[164:167], v[128:131], v[184:187], 0
	v_mfma_f32_16x16x32_bf16 v[160:163], v[152:155], v[184:187], 0
	s_waitcnt lgkmcnt(5)
	v_mfma_f32_16x16x32_bf16 v[136:139], v[128:131], v[192:195], 0
	v_mfma_f32_16x16x32_bf16 v[132:135], v[152:155], v[192:195], 0
	s_waitcnt lgkmcnt(3)
	v_mfma_f32_16x16x32_bf16 v[116:119], v[128:131], v[200:203], 0
	v_mfma_f32_16x16x32_bf16 v[112:115], v[152:155], v[200:203], 0
	s_waitcnt lgkmcnt(1)
	v_mfma_f32_16x16x32_bf16 v[76:79], v[128:131], v[224:227], 0
	v_mfma_f32_16x16x32_bf16 v[72:75], v[152:155], v[224:227], 0
	v_mfma_f32_16x16x32_bf16 v[164:167], v[140:143], v[188:191], v[164:167]
	v_mfma_f32_16x16x32_bf16 v[160:163], v[156:159], v[188:191], v[160:163]
	v_mfma_f32_16x16x32_bf16 v[136:139], v[140:143], v[196:199], v[136:139]
	v_mfma_f32_16x16x32_bf16 v[132:135], v[156:159], v[196:199], v[132:135]
	v_mfma_f32_16x16x32_bf16 v[116:119], v[140:143], v[204:207], v[116:119]
	v_mfma_f32_16x16x32_bf16 v[112:115], v[156:159], v[204:207], v[112:115]
	s_waitcnt lgkmcnt(0)
	v_mfma_f32_16x16x32_bf16 v[76:79], v[140:143], v[228:231], v[76:79]
	v_mfma_f32_16x16x32_bf16 v[72:75], v[156:159], v[228:231], v[72:75]
	v_mfma_f32_16x16x32_bf16 v[148:151], v[168:171], v[184:187], 0
	v_mfma_f32_16x16x32_bf16 v[144:147], v[176:179], v[184:187], 0
	v_mfma_f32_16x16x32_bf16 v[124:127], v[168:171], v[192:195], 0
	v_mfma_f32_16x16x32_bf16 v[120:123], v[176:179], v[192:195], 0
	v_mfma_f32_16x16x32_bf16 v[108:111], v[168:171], v[200:203], 0
	v_mfma_f32_16x16x32_bf16 v[104:107], v[176:179], v[200:203], 0
	v_mfma_f32_16x16x32_bf16 v[68:71], v[168:171], v[224:227], 0
	v_mfma_f32_16x16x32_bf16 v[64:67], v[176:179], v[224:227], 0
	v_mfma_f32_16x16x32_bf16 v[148:151], v[172:175], v[188:191], v[148:151]
	v_mfma_f32_16x16x32_bf16 v[144:147], v[180:183], v[188:191], v[144:147]
	v_mfma_f32_16x16x32_bf16 v[124:127], v[172:175], v[196:199], v[124:127]
	v_mfma_f32_16x16x32_bf16 v[120:123], v[180:183], v[196:199], v[120:123]
	v_mfma_f32_16x16x32_bf16 v[108:111], v[172:175], v[204:207], v[108:111]
	v_mfma_f32_16x16x32_bf16 v[104:107], v[180:183], v[204:207], v[104:107]
	v_mfma_f32_16x16x32_bf16 v[68:71], v[172:175], v[228:231], v[68:71]
	v_mfma_f32_16x16x32_bf16 v[64:67], v[180:183], v[228:231], v[64:67]
	s_barrier
	ds_read_b128 v[184:187], v223 offset:16384
	ds_read_b128 v[188:191], v223 offset:17408
	ds_read_b128 v[192:195], v223 offset:18432
	ds_read_b128 v[196:199], v223 offset:19456
	ds_read_b128 v[200:203], v223 offset:20480
	ds_read_b128 v[204:207], v223 offset:21504
	ds_read_b128 v[224:227], v223 offset:22528
	ds_read_b128 v[228:231], v223 offset:23552
	s_mov_b32 m0, s55
	s_nop 0
	buffer_load_dwordx4 v220, s[48:51], s12 offen lds
	s_add_i32 s14, s12, 0x80000
	s_mov_b32 m0, s76
	s_nop 0
	buffer_load_dwordx4 v221, s[48:51], s12 offen lds
	s_nop 0
	s_mov_b32 m0, s77
	s_nop 0
	buffer_load_dwordx4 v220, s[48:51], s14 offen lds
	s_nop 0
	s_mov_b32 m0, s78
	s_nop 0
	buffer_load_dwordx4 v221, s[48:51], s14 offen lds
	s_nop 0
	s_mov_b32 m0, s31
	s_nop 0
	buffer_load_dwordx4 v220, s[64:67], s13 offen lds
	s_nop 0
	s_mov_b32 m0, s79
	s_nop 0
	buffer_load_dwordx4 v221, s[64:67], s13 offen lds
	s_waitcnt vmcnt(24)
	s_waitcnt lgkmcnt(0)
	s_barrier
	s_waitcnt lgkmcnt(7)
	v_mfma_f32_16x16x32_bf16 v[60:63], v[128:131], v[184:187], 0
	v_mfma_f32_16x16x32_bf16 v[56:59], v[152:155], v[184:187], 0
	s_waitcnt lgkmcnt(5)
	v_mfma_f32_16x16x32_bf16 v[44:47], v[128:131], v[192:195], 0
	v_mfma_f32_16x16x32_bf16 v[40:43], v[152:155], v[192:195], 0
	s_waitcnt lgkmcnt(3)
	v_mfma_f32_16x16x32_bf16 v[28:31], v[128:131], v[200:203], 0
	v_mfma_f32_16x16x32_bf16 v[24:27], v[152:155], v[200:203], 0
	s_waitcnt lgkmcnt(1)
	v_mfma_f32_16x16x32_bf16 v[12:15], v[128:131], v[224:227], 0
	v_mfma_f32_16x16x32_bf16 v[8:11], v[152:155], v[224:227], 0
	v_mfma_f32_16x16x32_bf16 v[60:63], v[140:143], v[188:191], v[60:63]
	v_mfma_f32_16x16x32_bf16 v[56:59], v[156:159], v[188:191], v[56:59]
	v_mfma_f32_16x16x32_bf16 v[44:47], v[140:143], v[196:199], v[44:47]
	v_mfma_f32_16x16x32_bf16 v[40:43], v[156:159], v[196:199], v[40:43]
	v_mfma_f32_16x16x32_bf16 v[28:31], v[140:143], v[204:207], v[28:31]
	v_mfma_f32_16x16x32_bf16 v[24:27], v[156:159], v[204:207], v[24:27]
	s_waitcnt lgkmcnt(0)
	v_mfma_f32_16x16x32_bf16 v[12:15], v[140:143], v[228:231], v[12:15]
	v_mfma_f32_16x16x32_bf16 v[8:11], v[156:159], v[228:231], v[8:11]
	v_mfma_f32_16x16x32_bf16 v[52:55], v[168:171], v[184:187], 0
	v_mfma_f32_16x16x32_bf16 v[48:51], v[176:179], v[184:187], 0
	v_mfma_f32_16x16x32_bf16 v[36:39], v[168:171], v[192:195], 0
	v_mfma_f32_16x16x32_bf16 v[32:35], v[176:179], v[192:195], 0
	v_mfma_f32_16x16x32_bf16 v[20:23], v[168:171], v[200:203], 0
	v_mfma_f32_16x16x32_bf16 v[16:19], v[176:179], v[200:203], 0
	v_mfma_f32_16x16x32_bf16 v[4:7], v[168:171], v[224:227], 0
	v_mfma_f32_16x16x32_bf16 v[0:3], v[176:179], v[224:227], 0
	v_mfma_f32_16x16x32_bf16 v[52:55], v[172:175], v[188:191], v[52:55]
	v_mfma_f32_16x16x32_bf16 v[48:51], v[180:183], v[188:191], v[48:51]
	v_mfma_f32_16x16x32_bf16 v[36:39], v[172:175], v[196:199], v[36:39]
	v_mfma_f32_16x16x32_bf16 v[32:35], v[180:183], v[196:199], v[32:35]
	v_mfma_f32_16x16x32_bf16 v[20:23], v[172:175], v[204:207], v[20:23]
	v_mfma_f32_16x16x32_bf16 v[16:19], v[180:183], v[204:207], v[16:19]
	v_mfma_f32_16x16x32_bf16 v[4:7], v[172:175], v[228:231], v[4:7]
	v_mfma_f32_16x16x32_bf16 v[0:3], v[180:183], v[228:231], v[0:3]
	s_barrier
	v_add_u32_e32 v156, 0x18000, v222
	v_add_u32_e32 v180, 0x1c000, v222
	ds_read_b128 v[128:131], v156
	ds_read_b128 v[140:143], v156 offset:1024
	ds_read_b128 v[152:155], v156 offset:2048
	ds_read_b128 v[156:159], v156 offset:3072
	ds_read_b128 v[168:171], v180
	ds_read_b128 v[172:175], v180 offset:1024
	ds_read_b128 v[176:179], v180 offset:2048
	ds_read_b128 v[180:183], v180 offset:3072
	ds_read_b128 v[184:187], v223 offset:32768
	ds_read_b128 v[188:191], v223 offset:33792
	ds_read_b128 v[192:195], v223 offset:34816
	ds_read_b128 v[196:199], v223 offset:35840
	ds_read_b128 v[200:203], v223 offset:36864
	ds_read_b128 v[204:207], v223 offset:37888
	ds_read_b128 v[224:227], v223 offset:38912
	ds_read_b128 v[228:231], v223 offset:39936
	s_add_i32 s13, s13, 0x80000
	s_mov_b32 m0, s82
	s_nop 0
	buffer_load_dwordx4 v220, s[64:67], s13 offen lds
	s_nop 0
	s_mov_b32 m0, s83
	s_nop 0
	buffer_load_dwordx4 v221, s[64:67], s13 offen lds
	s_waitcnt vmcnt(8)
	s_waitcnt lgkmcnt(0)
	s_barrier
	s_waitcnt lgkmcnt(7)
	v_mfma_f32_16x16x32_bf16 v[164:167], v[128:131], v[184:187], v[164:167]
	v_mfma_f32_16x16x32_bf16 v[160:163], v[152:155], v[184:187], v[160:163]
	s_waitcnt lgkmcnt(5)
	v_mfma_f32_16x16x32_bf16 v[136:139], v[128:131], v[192:195], v[136:139]
	v_mfma_f32_16x16x32_bf16 v[132:135], v[152:155], v[192:195], v[132:135]
	s_waitcnt lgkmcnt(3)
	v_mfma_f32_16x16x32_bf16 v[116:119], v[128:131], v[200:203], v[116:119]
	v_mfma_f32_16x16x32_bf16 v[112:115], v[152:155], v[200:203], v[112:115]
	s_waitcnt lgkmcnt(1)
	v_mfma_f32_16x16x32_bf16 v[76:79], v[128:131], v[224:227], v[76:79]
	v_mfma_f32_16x16x32_bf16 v[72:75], v[152:155], v[224:227], v[72:75]
	v_mfma_f32_16x16x32_bf16 v[164:167], v[140:143], v[188:191], v[164:167]
	v_mfma_f32_16x16x32_bf16 v[160:163], v[156:159], v[188:191], v[160:163]
	v_mfma_f32_16x16x32_bf16 v[136:139], v[140:143], v[196:199], v[136:139]
	v_mfma_f32_16x16x32_bf16 v[132:135], v[156:159], v[196:199], v[132:135]
	v_mfma_f32_16x16x32_bf16 v[116:119], v[140:143], v[204:207], v[116:119]
	v_mfma_f32_16x16x32_bf16 v[112:115], v[156:159], v[204:207], v[112:115]
	s_waitcnt lgkmcnt(0)
	v_mfma_f32_16x16x32_bf16 v[76:79], v[140:143], v[228:231], v[76:79]
	v_mfma_f32_16x16x32_bf16 v[72:75], v[156:159], v[228:231], v[72:75]
	v_mfma_f32_16x16x32_bf16 v[148:151], v[168:171], v[184:187], v[148:151]
	v_mfma_f32_16x16x32_bf16 v[144:147], v[176:179], v[184:187], v[144:147]
	v_mfma_f32_16x16x32_bf16 v[124:127], v[168:171], v[192:195], v[124:127]
	v_mfma_f32_16x16x32_bf16 v[120:123], v[176:179], v[192:195], v[120:123]
	v_mfma_f32_16x16x32_bf16 v[108:111], v[168:171], v[200:203], v[108:111]
	v_mfma_f32_16x16x32_bf16 v[104:107], v[176:179], v[200:203], v[104:107]
	v_mfma_f32_16x16x32_bf16 v[68:71], v[168:171], v[224:227], v[68:71]
	v_mfma_f32_16x16x32_bf16 v[64:67], v[176:179], v[224:227], v[64:67]
	v_mfma_f32_16x16x32_bf16 v[148:151], v[172:175], v[188:191], v[148:151]
	v_mfma_f32_16x16x32_bf16 v[144:147], v[180:183], v[188:191], v[144:147]
	v_mfma_f32_16x16x32_bf16 v[124:127], v[172:175], v[196:199], v[124:127]
	v_mfma_f32_16x16x32_bf16 v[120:123], v[180:183], v[196:199], v[120:123]
	v_mfma_f32_16x16x32_bf16 v[108:111], v[172:175], v[204:207], v[108:111]
	v_mfma_f32_16x16x32_bf16 v[104:107], v[180:183], v[204:207], v[104:107]
	v_mfma_f32_16x16x32_bf16 v[68:71], v[172:175], v[228:231], v[68:71]
	v_mfma_f32_16x16x32_bf16 v[64:67], v[180:183], v[228:231], v[64:67]
	s_barrier
	ds_read_b128 v[184:187], v223 offset:49152
	ds_read_b128 v[188:191], v223 offset:50176
	ds_read_b128 v[192:195], v223 offset:51200
	ds_read_b128 v[196:199], v223 offset:52224
	ds_read_b128 v[200:203], v223 offset:53248
	ds_read_b128 v[204:207], v223 offset:54272
	ds_read_b128 v[224:227], v223 offset:55296
	ds_read_b128 v[228:231], v223 offset:56320
	s_or_b32 s13, s12, 0x4000
	s_mov_b32 m0, s34
	s_nop 0
	buffer_load_dwordx4 v220, s[48:51], s13 offen lds
	s_add_i32 s12, s12, 0x84000
	s_mov_b32 m0, s84
	s_nop 0
	buffer_load_dwordx4 v221, s[48:51], s13 offen lds
	s_nop 0
	s_mov_b32 m0, s87
	s_nop 0
	buffer_load_dwordx4 v220, s[48:51], s12 offen lds
	s_nop 0
	s_mov_b32 m0, s88
	s_nop 0
	buffer_load_dwordx4 v221, s[48:51], s12 offen lds
	s_nop 0
	s_mov_b32 m0, s85
	s_nop 0
	buffer_load_dwordx4 v220, s[64:67], s11 offen lds
	s_nop 0
	s_mov_b32 m0, s86
	s_nop 0
	buffer_load_dwordx4 v221, s[64:67], s11 offen lds
	s_waitcnt vmcnt(8)
	s_waitcnt lgkmcnt(0)
	s_barrier
	s_waitcnt lgkmcnt(7)
	v_mfma_f32_16x16x32_bf16 v[60:63], v[128:131], v[184:187], v[60:63]
	v_mfma_f32_16x16x32_bf16 v[56:59], v[152:155], v[184:187], v[56:59]
	s_waitcnt lgkmcnt(5)
	v_mfma_f32_16x16x32_bf16 v[44:47], v[128:131], v[192:195], v[44:47]
	v_mfma_f32_16x16x32_bf16 v[40:43], v[152:155], v[192:195], v[40:43]
	s_waitcnt lgkmcnt(3)
	v_mfma_f32_16x16x32_bf16 v[28:31], v[128:131], v[200:203], v[28:31]
	v_mfma_f32_16x16x32_bf16 v[24:27], v[152:155], v[200:203], v[24:27]
	s_waitcnt lgkmcnt(1)
	v_mfma_f32_16x16x32_bf16 v[12:15], v[128:131], v[224:227], v[12:15]
	v_mfma_f32_16x16x32_bf16 v[8:11], v[152:155], v[224:227], v[8:11]
	v_mfma_f32_16x16x32_bf16 v[60:63], v[140:143], v[188:191], v[60:63]
	v_mfma_f32_16x16x32_bf16 v[56:59], v[156:159], v[188:191], v[56:59]
	v_mfma_f32_16x16x32_bf16 v[44:47], v[140:143], v[196:199], v[44:47]
	v_mfma_f32_16x16x32_bf16 v[40:43], v[156:159], v[196:199], v[40:43]
	v_mfma_f32_16x16x32_bf16 v[28:31], v[140:143], v[204:207], v[28:31]
	v_mfma_f32_16x16x32_bf16 v[24:27], v[156:159], v[204:207], v[24:27]
	s_waitcnt lgkmcnt(0)
	v_mfma_f32_16x16x32_bf16 v[12:15], v[140:143], v[228:231], v[12:15]
	v_mfma_f32_16x16x32_bf16 v[8:11], v[156:159], v[228:231], v[8:11]
	v_mfma_f32_16x16x32_bf16 v[52:55], v[168:171], v[184:187], v[52:55]
	v_mfma_f32_16x16x32_bf16 v[48:51], v[176:179], v[184:187], v[48:51]
	v_mfma_f32_16x16x32_bf16 v[36:39], v[168:171], v[192:195], v[36:39]
	v_mfma_f32_16x16x32_bf16 v[32:35], v[176:179], v[192:195], v[32:35]
	v_mfma_f32_16x16x32_bf16 v[20:23], v[168:171], v[200:203], v[20:23]
	v_mfma_f32_16x16x32_bf16 v[16:19], v[176:179], v[200:203], v[16:19]
	v_mfma_f32_16x16x32_bf16 v[4:7], v[168:171], v[224:227], v[4:7]
	v_mfma_f32_16x16x32_bf16 v[0:3], v[176:179], v[224:227], v[0:3]
	v_mfma_f32_16x16x32_bf16 v[52:55], v[172:175], v[188:191], v[52:55]
	v_mfma_f32_16x16x32_bf16 v[48:51], v[180:183], v[188:191], v[48:51]
	v_mfma_f32_16x16x32_bf16 v[36:39], v[172:175], v[196:199], v[36:39]
	v_mfma_f32_16x16x32_bf16 v[32:35], v[180:183], v[196:199], v[32:35]
	v_mfma_f32_16x16x32_bf16 v[20:23], v[172:175], v[204:207], v[20:23]
	v_mfma_f32_16x16x32_bf16 v[16:19], v[180:183], v[204:207], v[16:19]
	v_mfma_f32_16x16x32_bf16 v[4:7], v[172:175], v[228:231], v[4:7]
	v_mfma_f32_16x16x32_bf16 v[0:3], v[180:183], v[228:231], v[0:3]
	s_barrier
	s_add_i32 s10, s10, 2
	s_add_i32 s8, s8, 0x8000
	s_add_i32 s9, s9, 0x8000
.LBB0_691:
	v_add_u32_e32 v156, 0x10000, v222
	v_add_u32_e32 v180, 0x14000, v222
	ds_read_b128 v[128:131], v156
	ds_read_b128 v[140:143], v156 offset:1024
	ds_read_b128 v[152:155], v156 offset:2048
	ds_read_b128 v[156:159], v156 offset:3072
	ds_read_b128 v[168:171], v180
	ds_read_b128 v[172:175], v180 offset:1024
	ds_read_b128 v[176:179], v180 offset:2048
	ds_read_b128 v[180:183], v180 offset:3072
	s_add_i32 s11, s8, 0xfff84000
	s_cmp_eq_u32 s10, 28
	s_cselect_b32 s13, s6, s11
	s_cselect_b32 s12, s7, s9
	s_or_b32 s11, s13, 0x4000
	ds_read_b128 v[184:187], v223
	ds_read_b128 v[188:191], v223 offset:1024
	ds_read_b128 v[192:195], v223 offset:2048
	ds_read_b128 v[196:199], v223 offset:3072
	ds_read_b128 v[200:203], v223 offset:4096
	ds_read_b128 v[204:207], v223 offset:5120
	ds_read_b128 v[224:227], v223 offset:6144
	ds_read_b128 v[228:231], v223 offset:7168
	s_mov_b32 m0, s89
	s_nop 0
	buffer_load_dwordx4 v220, s[64:67], s8 offen lds
	s_nop 0
	s_mov_b32 m0, s91
	s_nop 0
	buffer_load_dwordx4 v221, s[64:67], s8 offen lds
	s_waitcnt vmcnt(8)
	s_waitcnt lgkmcnt(0)
	s_barrier
	s_waitcnt lgkmcnt(7)
	v_mfma_f32_16x16x32_bf16 v[164:167], v[128:131], v[184:187], v[164:167]
	v_mfma_f32_16x16x32_bf16 v[160:163], v[152:155], v[184:187], v[160:163]
	s_waitcnt lgkmcnt(5)
	v_mfma_f32_16x16x32_bf16 v[136:139], v[128:131], v[192:195], v[136:139]
	v_mfma_f32_16x16x32_bf16 v[132:135], v[152:155], v[192:195], v[132:135]
	s_waitcnt lgkmcnt(3)
	v_mfma_f32_16x16x32_bf16 v[116:119], v[128:131], v[200:203], v[116:119]
	v_mfma_f32_16x16x32_bf16 v[112:115], v[152:155], v[200:203], v[112:115]
	s_waitcnt lgkmcnt(1)
	v_mfma_f32_16x16x32_bf16 v[76:79], v[128:131], v[224:227], v[76:79]
	v_mfma_f32_16x16x32_bf16 v[72:75], v[152:155], v[224:227], v[72:75]
	v_mfma_f32_16x16x32_bf16 v[164:167], v[140:143], v[188:191], v[164:167]
	v_mfma_f32_16x16x32_bf16 v[160:163], v[156:159], v[188:191], v[160:163]
	v_mfma_f32_16x16x32_bf16 v[136:139], v[140:143], v[196:199], v[136:139]
	v_mfma_f32_16x16x32_bf16 v[132:135], v[156:159], v[196:199], v[132:135]
	v_mfma_f32_16x16x32_bf16 v[116:119], v[140:143], v[204:207], v[116:119]
	v_mfma_f32_16x16x32_bf16 v[112:115], v[156:159], v[204:207], v[112:115]
	s_waitcnt lgkmcnt(0)
	v_mfma_f32_16x16x32_bf16 v[76:79], v[140:143], v[228:231], v[76:79]
	v_mfma_f32_16x16x32_bf16 v[72:75], v[156:159], v[228:231], v[72:75]
	v_mfma_f32_16x16x32_bf16 v[148:151], v[168:171], v[184:187], v[148:151]
	v_mfma_f32_16x16x32_bf16 v[144:147], v[176:179], v[184:187], v[144:147]
	v_mfma_f32_16x16x32_bf16 v[124:127], v[168:171], v[192:195], v[124:127]
	v_mfma_f32_16x16x32_bf16 v[120:123], v[176:179], v[192:195], v[120:123]
	v_mfma_f32_16x16x32_bf16 v[108:111], v[168:171], v[200:203], v[108:111]
	v_mfma_f32_16x16x32_bf16 v[104:107], v[176:179], v[200:203], v[104:107]
	v_mfma_f32_16x16x32_bf16 v[68:71], v[168:171], v[224:227], v[68:71]
	v_mfma_f32_16x16x32_bf16 v[64:67], v[176:179], v[224:227], v[64:67]
	v_mfma_f32_16x16x32_bf16 v[148:151], v[172:175], v[188:191], v[148:151]
	v_mfma_f32_16x16x32_bf16 v[144:147], v[180:183], v[188:191], v[144:147]
	v_mfma_f32_16x16x32_bf16 v[124:127], v[172:175], v[196:199], v[124:127]
	v_mfma_f32_16x16x32_bf16 v[120:123], v[180:183], v[196:199], v[120:123]
	v_mfma_f32_16x16x32_bf16 v[108:111], v[172:175], v[204:207], v[108:111]
	v_mfma_f32_16x16x32_bf16 v[104:107], v[180:183], v[204:207], v[104:107]
	v_mfma_f32_16x16x32_bf16 v[68:71], v[172:175], v[228:231], v[68:71]
	v_mfma_f32_16x16x32_bf16 v[64:67], v[180:183], v[228:231], v[64:67]
	s_barrier
	ds_read_b128 v[184:187], v223 offset:16384
	ds_read_b128 v[188:191], v223 offset:17408
	ds_read_b128 v[192:195], v223 offset:18432
	ds_read_b128 v[196:199], v223 offset:19456
	ds_read_b128 v[200:203], v223 offset:20480
	ds_read_b128 v[204:207], v223 offset:21504
	ds_read_b128 v[224:227], v223 offset:22528
	ds_read_b128 v[228:231], v223 offset:23552
	s_mov_b32 m0, s55
	s_nop 0
	buffer_load_dwordx4 v220, s[48:51], s12 offen lds
	s_add_i32 s14, s12, 0x80000
	s_mov_b32 m0, s76
	s_nop 0
	buffer_load_dwordx4 v221, s[48:51], s12 offen lds
	s_nop 0
	s_mov_b32 m0, s77
	s_nop 0
	buffer_load_dwordx4 v220, s[48:51], s14 offen lds
	s_nop 0
	s_mov_b32 m0, s78
	s_nop 0
	buffer_load_dwordx4 v221, s[48:51], s14 offen lds
	s_nop 0
	s_mov_b32 m0, s31
	s_nop 0
	buffer_load_dwordx4 v220, s[64:67], s13 offen lds
	s_nop 0
	s_mov_b32 m0, s79
	s_nop 0
	buffer_load_dwordx4 v221, s[64:67], s13 offen lds
	s_waitcnt vmcnt(8)
	s_waitcnt lgkmcnt(0)
	s_barrier
	s_waitcnt lgkmcnt(7)
	v_mfma_f32_16x16x32_bf16 v[60:63], v[128:131], v[184:187], v[60:63]
	v_mfma_f32_16x16x32_bf16 v[56:59], v[152:155], v[184:187], v[56:59]
	s_waitcnt lgkmcnt(5)
	v_mfma_f32_16x16x32_bf16 v[44:47], v[128:131], v[192:195], v[44:47]
	v_mfma_f32_16x16x32_bf16 v[40:43], v[152:155], v[192:195], v[40:43]
	s_waitcnt lgkmcnt(3)
	v_mfma_f32_16x16x32_bf16 v[28:31], v[128:131], v[200:203], v[28:31]
	v_mfma_f32_16x16x32_bf16 v[24:27], v[152:155], v[200:203], v[24:27]
	s_waitcnt lgkmcnt(1)
	v_mfma_f32_16x16x32_bf16 v[12:15], v[128:131], v[224:227], v[12:15]
	v_mfma_f32_16x16x32_bf16 v[8:11], v[152:155], v[224:227], v[8:11]
	v_mfma_f32_16x16x32_bf16 v[60:63], v[140:143], v[188:191], v[60:63]
	v_mfma_f32_16x16x32_bf16 v[56:59], v[156:159], v[188:191], v[56:59]
	v_mfma_f32_16x16x32_bf16 v[44:47], v[140:143], v[196:199], v[44:47]
	v_mfma_f32_16x16x32_bf16 v[40:43], v[156:159], v[196:199], v[40:43]
	v_mfma_f32_16x16x32_bf16 v[28:31], v[140:143], v[204:207], v[28:31]
	v_mfma_f32_16x16x32_bf16 v[24:27], v[156:159], v[204:207], v[24:27]
	s_waitcnt lgkmcnt(0)
	v_mfma_f32_16x16x32_bf16 v[12:15], v[140:143], v[228:231], v[12:15]
	v_mfma_f32_16x16x32_bf16 v[8:11], v[156:159], v[228:231], v[8:11]
	v_mfma_f32_16x16x32_bf16 v[52:55], v[168:171], v[184:187], v[52:55]
	v_mfma_f32_16x16x32_bf16 v[48:51], v[176:179], v[184:187], v[48:51]
	v_mfma_f32_16x16x32_bf16 v[36:39], v[168:171], v[192:195], v[36:39]
	v_mfma_f32_16x16x32_bf16 v[32:35], v[176:179], v[192:195], v[32:35]
	v_mfma_f32_16x16x32_bf16 v[20:23], v[168:171], v[200:203], v[20:23]
	v_mfma_f32_16x16x32_bf16 v[16:19], v[176:179], v[200:203], v[16:19]
	v_mfma_f32_16x16x32_bf16 v[4:7], v[168:171], v[224:227], v[4:7]
	v_mfma_f32_16x16x32_bf16 v[0:3], v[176:179], v[224:227], v[0:3]
	v_mfma_f32_16x16x32_bf16 v[52:55], v[172:175], v[188:191], v[52:55]
	v_mfma_f32_16x16x32_bf16 v[48:51], v[180:183], v[188:191], v[48:51]
	v_mfma_f32_16x16x32_bf16 v[36:39], v[172:175], v[196:199], v[36:39]
	v_mfma_f32_16x16x32_bf16 v[32:35], v[180:183], v[196:199], v[32:35]
	v_mfma_f32_16x16x32_bf16 v[20:23], v[172:175], v[204:207], v[20:23]
	v_mfma_f32_16x16x32_bf16 v[16:19], v[180:183], v[204:207], v[16:19]
	v_mfma_f32_16x16x32_bf16 v[4:7], v[172:175], v[228:231], v[4:7]
	v_mfma_f32_16x16x32_bf16 v[0:3], v[180:183], v[228:231], v[0:3]
	s_barrier
	v_add_u32_e32 v156, 0x18000, v222
	v_add_u32_e32 v180, 0x1c000, v222
	ds_read_b128 v[128:131], v156
	ds_read_b128 v[140:143], v156 offset:1024
	ds_read_b128 v[152:155], v156 offset:2048
	ds_read_b128 v[156:159], v156 offset:3072
	ds_read_b128 v[168:171], v180
	ds_read_b128 v[172:175], v180 offset:1024
	ds_read_b128 v[176:179], v180 offset:2048
	ds_read_b128 v[180:183], v180 offset:3072
	ds_read_b128 v[184:187], v223 offset:32768
	ds_read_b128 v[188:191], v223 offset:33792
	ds_read_b128 v[192:195], v223 offset:34816
	ds_read_b128 v[196:199], v223 offset:35840
	ds_read_b128 v[200:203], v223 offset:36864
	ds_read_b128 v[204:207], v223 offset:37888
	ds_read_b128 v[224:227], v223 offset:38912
	ds_read_b128 v[228:231], v223 offset:39936
	s_add_i32 s13, s13, 0x80000
	s_mov_b32 m0, s82
	s_nop 0
	buffer_load_dwordx4 v220, s[64:67], s13 offen lds
	s_nop 0
	s_mov_b32 m0, s83
	s_nop 0
	buffer_load_dwordx4 v221, s[64:67], s13 offen lds
	s_waitcnt vmcnt(8)
	s_waitcnt lgkmcnt(0)
	s_barrier
	s_waitcnt lgkmcnt(7)
	v_mfma_f32_16x16x32_bf16 v[164:167], v[128:131], v[184:187], v[164:167]
	v_mfma_f32_16x16x32_bf16 v[160:163], v[152:155], v[184:187], v[160:163]
	s_waitcnt lgkmcnt(5)
	v_mfma_f32_16x16x32_bf16 v[136:139], v[128:131], v[192:195], v[136:139]
	v_mfma_f32_16x16x32_bf16 v[132:135], v[152:155], v[192:195], v[132:135]
	s_waitcnt lgkmcnt(3)
	v_mfma_f32_16x16x32_bf16 v[116:119], v[128:131], v[200:203], v[116:119]
	v_mfma_f32_16x16x32_bf16 v[112:115], v[152:155], v[200:203], v[112:115]
	s_waitcnt lgkmcnt(1)
	v_mfma_f32_16x16x32_bf16 v[76:79], v[128:131], v[224:227], v[76:79]
	v_mfma_f32_16x16x32_bf16 v[72:75], v[152:155], v[224:227], v[72:75]
	v_mfma_f32_16x16x32_bf16 v[164:167], v[140:143], v[188:191], v[164:167]
	v_mfma_f32_16x16x32_bf16 v[160:163], v[156:159], v[188:191], v[160:163]
	v_mfma_f32_16x16x32_bf16 v[136:139], v[140:143], v[196:199], v[136:139]
	v_mfma_f32_16x16x32_bf16 v[132:135], v[156:159], v[196:199], v[132:135]
	v_mfma_f32_16x16x32_bf16 v[116:119], v[140:143], v[204:207], v[116:119]
	v_mfma_f32_16x16x32_bf16 v[112:115], v[156:159], v[204:207], v[112:115]
	s_waitcnt lgkmcnt(0)
	v_mfma_f32_16x16x32_bf16 v[76:79], v[140:143], v[228:231], v[76:79]
	v_mfma_f32_16x16x32_bf16 v[72:75], v[156:159], v[228:231], v[72:75]
	v_mfma_f32_16x16x32_bf16 v[148:151], v[168:171], v[184:187], v[148:151]
	v_mfma_f32_16x16x32_bf16 v[144:147], v[176:179], v[184:187], v[144:147]
	v_mfma_f32_16x16x32_bf16 v[124:127], v[168:171], v[192:195], v[124:127]
	v_mfma_f32_16x16x32_bf16 v[120:123], v[176:179], v[192:195], v[120:123]
	v_mfma_f32_16x16x32_bf16 v[108:111], v[168:171], v[200:203], v[108:111]
	v_mfma_f32_16x16x32_bf16 v[104:107], v[176:179], v[200:203], v[104:107]
	v_mfma_f32_16x16x32_bf16 v[68:71], v[168:171], v[224:227], v[68:71]
	v_mfma_f32_16x16x32_bf16 v[64:67], v[176:179], v[224:227], v[64:67]
	v_mfma_f32_16x16x32_bf16 v[148:151], v[172:175], v[188:191], v[148:151]
	v_mfma_f32_16x16x32_bf16 v[144:147], v[180:183], v[188:191], v[144:147]
	v_mfma_f32_16x16x32_bf16 v[124:127], v[172:175], v[196:199], v[124:127]
	v_mfma_f32_16x16x32_bf16 v[120:123], v[180:183], v[196:199], v[120:123]
	v_mfma_f32_16x16x32_bf16 v[108:111], v[172:175], v[204:207], v[108:111]
	v_mfma_f32_16x16x32_bf16 v[104:107], v[180:183], v[204:207], v[104:107]
	v_mfma_f32_16x16x32_bf16 v[68:71], v[172:175], v[228:231], v[68:71]
	v_mfma_f32_16x16x32_bf16 v[64:67], v[180:183], v[228:231], v[64:67]
	s_barrier
	ds_read_b128 v[184:187], v223 offset:49152
	ds_read_b128 v[188:191], v223 offset:50176
	ds_read_b128 v[192:195], v223 offset:51200
	ds_read_b128 v[196:199], v223 offset:52224
	ds_read_b128 v[200:203], v223 offset:53248
	ds_read_b128 v[204:207], v223 offset:54272
	ds_read_b128 v[224:227], v223 offset:55296
	ds_read_b128 v[228:231], v223 offset:56320
	s_or_b32 s13, s12, 0x4000
	s_mov_b32 m0, s34
	s_nop 0
	buffer_load_dwordx4 v220, s[48:51], s13 offen lds
	s_add_i32 s12, s12, 0x84000
	s_mov_b32 m0, s84
	s_nop 0
	buffer_load_dwordx4 v221, s[48:51], s13 offen lds
	s_nop 0
	s_mov_b32 m0, s87
	s_nop 0
	buffer_load_dwordx4 v220, s[48:51], s12 offen lds
	s_nop 0
	s_mov_b32 m0, s88
	s_nop 0
	buffer_load_dwordx4 v221, s[48:51], s12 offen lds
	s_nop 0
	s_mov_b32 m0, s85
	s_nop 0
	buffer_load_dwordx4 v220, s[64:67], s11 offen lds
	s_nop 0
	s_mov_b32 m0, s86
	s_nop 0
	buffer_load_dwordx4 v221, s[64:67], s11 offen lds
	s_waitcnt vmcnt(8)
	s_waitcnt lgkmcnt(0)
	s_barrier
	s_waitcnt lgkmcnt(7)
	v_mfma_f32_16x16x32_bf16 v[60:63], v[128:131], v[184:187], v[60:63]
	v_mfma_f32_16x16x32_bf16 v[56:59], v[152:155], v[184:187], v[56:59]
	s_waitcnt lgkmcnt(5)
	v_mfma_f32_16x16x32_bf16 v[44:47], v[128:131], v[192:195], v[44:47]
	v_mfma_f32_16x16x32_bf16 v[40:43], v[152:155], v[192:195], v[40:43]
	s_waitcnt lgkmcnt(3)
	v_mfma_f32_16x16x32_bf16 v[28:31], v[128:131], v[200:203], v[28:31]
	v_mfma_f32_16x16x32_bf16 v[24:27], v[152:155], v[200:203], v[24:27]
	s_waitcnt lgkmcnt(1)
	v_mfma_f32_16x16x32_bf16 v[12:15], v[128:131], v[224:227], v[12:15]
	v_mfma_f32_16x16x32_bf16 v[8:11], v[152:155], v[224:227], v[8:11]
	v_mfma_f32_16x16x32_bf16 v[60:63], v[140:143], v[188:191], v[60:63]
	v_mfma_f32_16x16x32_bf16 v[56:59], v[156:159], v[188:191], v[56:59]
	v_mfma_f32_16x16x32_bf16 v[44:47], v[140:143], v[196:199], v[44:47]
	v_mfma_f32_16x16x32_bf16 v[40:43], v[156:159], v[196:199], v[40:43]
	v_mfma_f32_16x16x32_bf16 v[28:31], v[140:143], v[204:207], v[28:31]
	v_mfma_f32_16x16x32_bf16 v[24:27], v[156:159], v[204:207], v[24:27]
	s_waitcnt lgkmcnt(0)
	v_mfma_f32_16x16x32_bf16 v[12:15], v[140:143], v[228:231], v[12:15]
	v_mfma_f32_16x16x32_bf16 v[8:11], v[156:159], v[228:231], v[8:11]
	v_mfma_f32_16x16x32_bf16 v[52:55], v[168:171], v[184:187], v[52:55]
	v_mfma_f32_16x16x32_bf16 v[48:51], v[176:179], v[184:187], v[48:51]
	v_mfma_f32_16x16x32_bf16 v[36:39], v[168:171], v[192:195], v[36:39]
	v_mfma_f32_16x16x32_bf16 v[32:35], v[176:179], v[192:195], v[32:35]
	v_mfma_f32_16x16x32_bf16 v[20:23], v[168:171], v[200:203], v[20:23]
	v_mfma_f32_16x16x32_bf16 v[16:19], v[176:179], v[200:203], v[16:19]
	v_mfma_f32_16x16x32_bf16 v[4:7], v[168:171], v[224:227], v[4:7]
	v_mfma_f32_16x16x32_bf16 v[0:3], v[176:179], v[224:227], v[0:3]
	v_mfma_f32_16x16x32_bf16 v[52:55], v[172:175], v[188:191], v[52:55]
	v_mfma_f32_16x16x32_bf16 v[48:51], v[180:183], v[188:191], v[48:51]
	v_mfma_f32_16x16x32_bf16 v[36:39], v[172:175], v[196:199], v[36:39]
	v_mfma_f32_16x16x32_bf16 v[32:35], v[180:183], v[196:199], v[32:35]
	v_mfma_f32_16x16x32_bf16 v[20:23], v[172:175], v[204:207], v[20:23]
	v_mfma_f32_16x16x32_bf16 v[16:19], v[180:183], v[204:207], v[16:19]
	v_mfma_f32_16x16x32_bf16 v[4:7], v[172:175], v[228:231], v[4:7]
	v_mfma_f32_16x16x32_bf16 v[0:3], v[180:183], v[228:231], v[0:3]
	s_barrier
	s_add_i32 s10, s10, 2
	s_add_i32 s8, s8, 0x8000
	s_add_i32 s9, s9, 0x8000
	s_cmp_gt_u32 s10, 29
	s_cbranch_scc0 .LBB0_691

.Lnb_p5:
	s_add_i32 s53, s37, 0xfff84000
	s_cmp_eq_u32 s52, 28
	s_cselect_b32 s56, s4, s53
	s_cselect_b32 s55, s5, s51
	s_or_b32 s53, s56, 0x4000
	s_mov_b32 m0, s41
	s_nop 0
	buffer_load_dwordx4 v166, s[24:27], s37 offen lds
	s_nop 0
	s_mov_b32 m0, s42
	s_nop 0
	buffer_load_dwordx4 v167, s[24:27], s37 offen lds
	s_waitcnt vmcnt(24)
	s_waitcnt lgkmcnt(0)
	s_barrier
	s_waitcnt lgkmcnt(7)
	v_mfma_f32_16x16x32_bf16 v[148:151], v[152:155], v[190:193], 0
	v_mfma_f32_16x16x32_bf16 v[140:143], v[160:163], v[190:193], 0
	s_waitcnt lgkmcnt(5)
	v_mfma_f32_16x16x32_bf16 v[132:135], v[152:155], v[198:201], 0
	v_mfma_f32_16x16x32_bf16 v[124:127], v[160:163], v[198:201], 0
	s_waitcnt lgkmcnt(3)
	v_mfma_f32_16x16x32_bf16 v[116:119], v[152:155], v[220:223], 0
	v_mfma_f32_16x16x32_bf16 v[108:111], v[160:163], v[220:223], 0
	s_waitcnt lgkmcnt(1)
	v_mfma_f32_16x16x32_bf16 v[76:79], v[152:155], v[228:231], 0
	v_mfma_f32_16x16x32_bf16 v[68:71], v[160:163], v[228:231], 0
	v_mfma_f32_16x16x32_bf16 v[148:151], v[156:159], v[194:197], v[148:151]
	v_mfma_f32_16x16x32_bf16 v[140:143], v[170:173], v[194:197], v[140:143]
	v_mfma_f32_16x16x32_bf16 v[132:135], v[156:159], v[202:205], v[132:135]
	v_mfma_f32_16x16x32_bf16 v[124:127], v[170:173], v[202:205], v[124:127]
	v_mfma_f32_16x16x32_bf16 v[116:119], v[156:159], v[224:227], v[116:119]
	v_mfma_f32_16x16x32_bf16 v[108:111], v[170:173], v[224:227], v[108:111]
	s_waitcnt lgkmcnt(0)
	v_mfma_f32_16x16x32_bf16 v[76:79], v[156:159], v[240:243], v[76:79]
	v_mfma_f32_16x16x32_bf16 v[68:71], v[170:173], v[240:243], v[68:71]
	v_mfma_f32_16x16x32_bf16 v[144:147], v[174:177], v[190:193], 0
	v_mfma_f32_16x16x32_bf16 v[136:139], v[182:185], v[190:193], 0
	v_mfma_f32_16x16x32_bf16 v[128:131], v[174:177], v[198:201], 0
	v_mfma_f32_16x16x32_bf16 v[120:123], v[182:185], v[198:201], 0
	v_mfma_f32_16x16x32_bf16 v[112:115], v[174:177], v[220:223], 0
	v_mfma_f32_16x16x32_bf16 v[104:107], v[182:185], v[220:223], 0
	v_mfma_f32_16x16x32_bf16 v[72:75], v[174:177], v[228:231], 0
	v_mfma_f32_16x16x32_bf16 v[64:67], v[182:185], v[228:231], 0
	v_mfma_f32_16x16x32_bf16 v[144:147], v[178:181], v[194:197], v[144:147]
	v_mfma_f32_16x16x32_bf16 v[136:139], v[186:189], v[194:197], v[136:139]
	v_mfma_f32_16x16x32_bf16 v[128:131], v[178:181], v[202:205], v[128:131]
	v_mfma_f32_16x16x32_bf16 v[120:123], v[186:189], v[202:205], v[120:123]
	v_mfma_f32_16x16x32_bf16 v[112:115], v[178:181], v[224:227], v[112:115]
	v_mfma_f32_16x16x32_bf16 v[104:107], v[186:189], v[224:227], v[104:107]
	v_mfma_f32_16x16x32_bf16 v[72:75], v[178:181], v[240:243], v[72:75]
	v_mfma_f32_16x16x32_bf16 v[64:67], v[186:189], v[240:243], v[64:67]
	s_barrier
	ds_read_b128 v[190:193], v169 offset:16384
	ds_read_b128 v[194:197], v169 offset:17408
	ds_read_b128 v[198:201], v169 offset:18432
	ds_read_b128 v[202:205], v169 offset:19456
	ds_read_b128 v[220:223], v169 offset:20480
	ds_read_b128 v[224:227], v169 offset:21504
	ds_read_b128 v[228:231], v169 offset:22528
	ds_read_b128 v[240:243], v169 offset:23552
	s_mov_b32 m0, s7
	s_nop 0
	buffer_load_dwordx4 v166, s[28:31], s55 offen lds
	s_add_i32 s57, s55, 0x80000
	s_mov_b32 m0, s8
	s_nop 0
	buffer_load_dwordx4 v167, s[28:31], s55 offen lds
	s_nop 0
	s_mov_b32 m0, s9
	s_nop 0
	buffer_load_dwordx4 v166, s[28:31], s57 offen lds
	s_nop 0
	s_mov_b32 m0, s10
	s_nop 0
	buffer_load_dwordx4 v167, s[28:31], s57 offen lds
	s_nop 0
	s_mov_b32 m0, s6
	s_nop 0
	buffer_load_dwordx4 v166, s[24:27], s56 offen lds
	s_nop 0
	s_mov_b32 m0, s11
	s_nop 0
	buffer_load_dwordx4 v167, s[24:27], s56 offen lds
	s_waitcnt vmcnt(24)
	s_waitcnt lgkmcnt(0)
	s_barrier
	s_waitcnt lgkmcnt(7)
	v_mfma_f32_16x16x32_bf16 v[60:63], v[152:155], v[190:193], 0
	v_mfma_f32_16x16x32_bf16 v[52:55], v[160:163], v[190:193], 0
	s_waitcnt lgkmcnt(5)
	v_mfma_f32_16x16x32_bf16 v[44:47], v[152:155], v[198:201], 0
	v_mfma_f32_16x16x32_bf16 v[36:39], v[160:163], v[198:201], 0
	s_waitcnt lgkmcnt(3)
	v_mfma_f32_16x16x32_bf16 v[28:31], v[152:155], v[220:223], 0
	v_mfma_f32_16x16x32_bf16 v[20:23], v[160:163], v[220:223], 0
	s_waitcnt lgkmcnt(1)
	v_mfma_f32_16x16x32_bf16 v[12:15], v[152:155], v[228:231], 0
	v_mfma_f32_16x16x32_bf16 v[4:7], v[160:163], v[228:231], 0
	v_mfma_f32_16x16x32_bf16 v[60:63], v[156:159], v[194:197], v[60:63]
	v_mfma_f32_16x16x32_bf16 v[52:55], v[170:173], v[194:197], v[52:55]
	v_mfma_f32_16x16x32_bf16 v[44:47], v[156:159], v[202:205], v[44:47]
	v_mfma_f32_16x16x32_bf16 v[36:39], v[170:173], v[202:205], v[36:39]
	v_mfma_f32_16x16x32_bf16 v[28:31], v[156:159], v[224:227], v[28:31]
	v_mfma_f32_16x16x32_bf16 v[20:23], v[170:173], v[224:227], v[20:23]
	s_waitcnt lgkmcnt(0)
	v_mfma_f32_16x16x32_bf16 v[12:15], v[156:159], v[240:243], v[12:15]
	v_mfma_f32_16x16x32_bf16 v[4:7], v[170:173], v[240:243], v[4:7]
	v_mfma_f32_16x16x32_bf16 v[56:59], v[174:177], v[190:193], 0
	v_mfma_f32_16x16x32_bf16 v[48:51], v[182:185], v[190:193], 0
	v_mfma_f32_16x16x32_bf16 v[40:43], v[174:177], v[198:201], 0
	v_mfma_f32_16x16x32_bf16 v[32:35], v[182:185], v[198:201], 0
	v_mfma_f32_16x16x32_bf16 v[24:27], v[174:177], v[220:223], 0
	v_mfma_f32_16x16x32_bf16 v[16:19], v[182:185], v[220:223], 0
	v_mfma_f32_16x16x32_bf16 v[8:11], v[174:177], v[228:231], 0
	v_mfma_f32_16x16x32_bf16 v[0:3], v[182:185], v[228:231], 0
	v_mfma_f32_16x16x32_bf16 v[56:59], v[178:181], v[194:197], v[56:59]
	v_mfma_f32_16x16x32_bf16 v[48:51], v[186:189], v[194:197], v[48:51]
	v_mfma_f32_16x16x32_bf16 v[40:43], v[178:181], v[202:205], v[40:43]
	v_mfma_f32_16x16x32_bf16 v[32:35], v[186:189], v[202:205], v[32:35]
	v_mfma_f32_16x16x32_bf16 v[24:27], v[178:181], v[224:227], v[24:27]
	v_mfma_f32_16x16x32_bf16 v[16:19], v[186:189], v[224:227], v[16:19]
	v_mfma_f32_16x16x32_bf16 v[8:11], v[178:181], v[240:243], v[8:11]
	v_mfma_f32_16x16x32_bf16 v[0:3], v[186:189], v[240:243], v[0:3]
	s_barrier
	v_add_u32_e32 v164, 0x18000, v168
	ds_read_b128 v[152:155], v164
	ds_read_b128 v[156:159], v164 offset:1024
	ds_read_b128 v[160:163], v164 offset:2048
	ds_read_b128 v[170:173], v164 offset:3072
	v_add_u32_e32 v164, 0x1c000, v168
	ds_read_b128 v[174:177], v164
	ds_read_b128 v[178:181], v164 offset:1024
	ds_read_b128 v[182:185], v164 offset:2048
	ds_read_b128 v[186:189], v164 offset:3072
	ds_read_b128 v[190:193], v169 offset:32768
	ds_read_b128 v[194:197], v169 offset:33792
	ds_read_b128 v[198:201], v169 offset:34816
	ds_read_b128 v[202:205], v169 offset:35840
	ds_read_b128 v[220:223], v169 offset:36864
	ds_read_b128 v[224:227], v169 offset:37888
	ds_read_b128 v[228:231], v169 offset:38912
	ds_read_b128 v[240:243], v169 offset:39936
	s_add_i32 s56, s56, 0x80000
	s_mov_b32 m0, s12
	s_nop 0
	buffer_load_dwordx4 v166, s[24:27], s56 offen lds
	s_nop 0
	s_mov_b32 m0, s13
	s_nop 0
	buffer_load_dwordx4 v167, s[24:27], s56 offen lds
	s_waitcnt vmcnt(8)
	s_waitcnt lgkmcnt(0)
	s_barrier
	s_waitcnt lgkmcnt(7)
	v_mfma_f32_16x16x32_bf16 v[148:151], v[152:155], v[190:193], v[148:151]
	v_mfma_f32_16x16x32_bf16 v[140:143], v[160:163], v[190:193], v[140:143]
	s_waitcnt lgkmcnt(5)
	v_mfma_f32_16x16x32_bf16 v[132:135], v[152:155], v[198:201], v[132:135]
	v_mfma_f32_16x16x32_bf16 v[124:127], v[160:163], v[198:201], v[124:127]
	s_waitcnt lgkmcnt(3)
	v_mfma_f32_16x16x32_bf16 v[116:119], v[152:155], v[220:223], v[116:119]
	v_mfma_f32_16x16x32_bf16 v[108:111], v[160:163], v[220:223], v[108:111]
	s_waitcnt lgkmcnt(1)
	v_mfma_f32_16x16x32_bf16 v[76:79], v[152:155], v[228:231], v[76:79]
	v_mfma_f32_16x16x32_bf16 v[68:71], v[160:163], v[228:231], v[68:71]
	v_mfma_f32_16x16x32_bf16 v[148:151], v[156:159], v[194:197], v[148:151]
	v_mfma_f32_16x16x32_bf16 v[140:143], v[170:173], v[194:197], v[140:143]
	v_mfma_f32_16x16x32_bf16 v[132:135], v[156:159], v[202:205], v[132:135]
	v_mfma_f32_16x16x32_bf16 v[124:127], v[170:173], v[202:205], v[124:127]
	v_mfma_f32_16x16x32_bf16 v[116:119], v[156:159], v[224:227], v[116:119]
	v_mfma_f32_16x16x32_bf16 v[108:111], v[170:173], v[224:227], v[108:111]
	s_waitcnt lgkmcnt(0)
	v_mfma_f32_16x16x32_bf16 v[76:79], v[156:159], v[240:243], v[76:79]
	v_mfma_f32_16x16x32_bf16 v[68:71], v[170:173], v[240:243], v[68:71]
	v_mfma_f32_16x16x32_bf16 v[144:147], v[174:177], v[190:193], v[144:147]
	v_mfma_f32_16x16x32_bf16 v[136:139], v[182:185], v[190:193], v[136:139]
	v_mfma_f32_16x16x32_bf16 v[128:131], v[174:177], v[198:201], v[128:131]
	v_mfma_f32_16x16x32_bf16 v[120:123], v[182:185], v[198:201], v[120:123]
	v_mfma_f32_16x16x32_bf16 v[112:115], v[174:177], v[220:223], v[112:115]
	v_mfma_f32_16x16x32_bf16 v[104:107], v[182:185], v[220:223], v[104:107]
	v_mfma_f32_16x16x32_bf16 v[72:75], v[174:177], v[228:231], v[72:75]
	v_mfma_f32_16x16x32_bf16 v[64:67], v[182:185], v[228:231], v[64:67]
	v_mfma_f32_16x16x32_bf16 v[144:147], v[178:181], v[194:197], v[144:147]
	v_mfma_f32_16x16x32_bf16 v[136:139], v[186:189], v[194:197], v[136:139]
	v_mfma_f32_16x16x32_bf16 v[128:131], v[178:181], v[202:205], v[128:131]
	v_mfma_f32_16x16x32_bf16 v[120:123], v[186:189], v[202:205], v[120:123]
	v_mfma_f32_16x16x32_bf16 v[112:115], v[178:181], v[224:227], v[112:115]
	v_mfma_f32_16x16x32_bf16 v[104:107], v[186:189], v[224:227], v[104:107]
	v_mfma_f32_16x16x32_bf16 v[72:75], v[178:181], v[240:243], v[72:75]
	v_mfma_f32_16x16x32_bf16 v[64:67], v[186:189], v[240:243], v[64:67]
	s_barrier
	ds_read_b128 v[190:193], v169 offset:49152
	ds_read_b128 v[194:197], v169 offset:50176
	ds_read_b128 v[198:201], v169 offset:51200
	ds_read_b128 v[202:205], v169 offset:52224
	ds_read_b128 v[220:223], v169 offset:53248
	ds_read_b128 v[224:227], v169 offset:54272
	ds_read_b128 v[228:231], v169 offset:55296
	ds_read_b128 v[240:243], v169 offset:56320
	s_or_b32 s56, s55, 0x4000
	s_mov_b32 m0, s16
	s_nop 0
	buffer_load_dwordx4 v166, s[28:31], s56 offen lds
	s_add_i32 s55, s55, 0x84000
	s_mov_b32 m0, s17
	s_nop 0
	buffer_load_dwordx4 v167, s[28:31], s56 offen lds
	s_nop 0
	s_mov_b32 m0, s34
	s_nop 0
	buffer_load_dwordx4 v166, s[28:31], s55 offen lds
	s_nop 0
	s_mov_b32 m0, s40
	s_nop 0
	buffer_load_dwordx4 v167, s[28:31], s55 offen lds
	s_nop 0
	s_mov_b32 m0, s18
	s_nop 0
	buffer_load_dwordx4 v166, s[24:27], s53 offen lds
	s_nop 0
	s_mov_b32 m0, s19
	s_nop 0
	buffer_load_dwordx4 v167, s[24:27], s53 offen lds
	s_waitcnt vmcnt(8)
	s_waitcnt lgkmcnt(0)
	s_barrier
	s_waitcnt lgkmcnt(7)
	v_mfma_f32_16x16x32_bf16 v[60:63], v[152:155], v[190:193], v[60:63]
	v_mfma_f32_16x16x32_bf16 v[52:55], v[160:163], v[190:193], v[52:55]
	s_waitcnt lgkmcnt(5)
	v_mfma_f32_16x16x32_bf16 v[44:47], v[152:155], v[198:201], v[44:47]
	v_mfma_f32_16x16x32_bf16 v[36:39], v[160:163], v[198:201], v[36:39]
	s_waitcnt lgkmcnt(3)
	v_mfma_f32_16x16x32_bf16 v[28:31], v[152:155], v[220:223], v[28:31]
	v_mfma_f32_16x16x32_bf16 v[20:23], v[160:163], v[220:223], v[20:23]
	s_waitcnt lgkmcnt(1)
	v_mfma_f32_16x16x32_bf16 v[12:15], v[152:155], v[228:231], v[12:15]
	v_mfma_f32_16x16x32_bf16 v[4:7], v[160:163], v[228:231], v[4:7]
	v_mfma_f32_16x16x32_bf16 v[60:63], v[156:159], v[194:197], v[60:63]
	v_mfma_f32_16x16x32_bf16 v[52:55], v[170:173], v[194:197], v[52:55]
	v_mfma_f32_16x16x32_bf16 v[44:47], v[156:159], v[202:205], v[44:47]
	v_mfma_f32_16x16x32_bf16 v[36:39], v[170:173], v[202:205], v[36:39]
	v_mfma_f32_16x16x32_bf16 v[28:31], v[156:159], v[224:227], v[28:31]
	v_mfma_f32_16x16x32_bf16 v[20:23], v[170:173], v[224:227], v[20:23]
	s_waitcnt lgkmcnt(0)
	v_mfma_f32_16x16x32_bf16 v[12:15], v[156:159], v[240:243], v[12:15]
	v_mfma_f32_16x16x32_bf16 v[4:7], v[170:173], v[240:243], v[4:7]
	v_mfma_f32_16x16x32_bf16 v[56:59], v[174:177], v[190:193], v[56:59]
	v_mfma_f32_16x16x32_bf16 v[48:51], v[182:185], v[190:193], v[48:51]
	v_mfma_f32_16x16x32_bf16 v[40:43], v[174:177], v[198:201], v[40:43]
	v_mfma_f32_16x16x32_bf16 v[32:35], v[182:185], v[198:201], v[32:35]
	v_mfma_f32_16x16x32_bf16 v[24:27], v[174:177], v[220:223], v[24:27]
	v_mfma_f32_16x16x32_bf16 v[16:19], v[182:185], v[220:223], v[16:19]
	v_mfma_f32_16x16x32_bf16 v[8:11], v[174:177], v[228:231], v[8:11]
	v_mfma_f32_16x16x32_bf16 v[0:3], v[182:185], v[228:231], v[0:3]
	v_mfma_f32_16x16x32_bf16 v[56:59], v[178:181], v[194:197], v[56:59]
	v_mfma_f32_16x16x32_bf16 v[48:51], v[186:189], v[194:197], v[48:51]
	v_mfma_f32_16x16x32_bf16 v[40:43], v[178:181], v[202:205], v[40:43]
	v_mfma_f32_16x16x32_bf16 v[32:35], v[186:189], v[202:205], v[32:35]
	v_mfma_f32_16x16x32_bf16 v[24:27], v[178:181], v[224:227], v[24:27]
	v_mfma_f32_16x16x32_bf16 v[16:19], v[186:189], v[224:227], v[16:19]
	v_mfma_f32_16x16x32_bf16 v[8:11], v[178:181], v[240:243], v[8:11]
	v_mfma_f32_16x16x32_bf16 v[0:3], v[186:189], v[240:243], v[0:3]
	s_barrier
	s_add_i32 s52, s52, 2
	s_add_i32 s37, s37, 0x8000
	s_add_i32 s51, s51, 0x8000
.LBB0_795:
	v_add_u32_e32 v164, 0x10000, v168
	ds_read_b128 v[152:155], v164
	ds_read_b128 v[156:159], v164 offset:1024
	ds_read_b128 v[160:163], v164 offset:2048
	ds_read_b128 v[170:173], v164 offset:3072
	v_add_u32_e32 v164, 0x14000, v168
	ds_read_b128 v[174:177], v164
	ds_read_b128 v[178:181], v164 offset:1024
	ds_read_b128 v[182:185], v164 offset:2048
	ds_read_b128 v[186:189], v164 offset:3072
	s_add_i32 s53, s37, 0xfff84000
	s_cmp_eq_u32 s52, 28
	s_cselect_b32 s56, s4, s53
	s_cselect_b32 s55, s5, s51
	s_or_b32 s53, s56, 0x4000
	ds_read_b128 v[190:193], v169
	ds_read_b128 v[194:197], v169 offset:1024
	ds_read_b128 v[198:201], v169 offset:2048
	ds_read_b128 v[202:205], v169 offset:3072
	ds_read_b128 v[220:223], v169 offset:4096
	ds_read_b128 v[224:227], v169 offset:5120
	ds_read_b128 v[228:231], v169 offset:6144
	ds_read_b128 v[240:243], v169 offset:7168
	s_mov_b32 m0, s41
	s_nop 0
	buffer_load_dwordx4 v166, s[24:27], s37 offen lds
	s_nop 0
	s_mov_b32 m0, s42
	s_nop 0
	buffer_load_dwordx4 v167, s[24:27], s37 offen lds
	s_waitcnt vmcnt(8)
	s_waitcnt lgkmcnt(0)
	s_barrier
	s_waitcnt lgkmcnt(7)
	v_mfma_f32_16x16x32_bf16 v[148:151], v[152:155], v[190:193], v[148:151]
	v_mfma_f32_16x16x32_bf16 v[140:143], v[160:163], v[190:193], v[140:143]
	s_waitcnt lgkmcnt(5)
	v_mfma_f32_16x16x32_bf16 v[132:135], v[152:155], v[198:201], v[132:135]
	v_mfma_f32_16x16x32_bf16 v[124:127], v[160:163], v[198:201], v[124:127]
	s_waitcnt lgkmcnt(3)
	v_mfma_f32_16x16x32_bf16 v[116:119], v[152:155], v[220:223], v[116:119]
	v_mfma_f32_16x16x32_bf16 v[108:111], v[160:163], v[220:223], v[108:111]
	s_waitcnt lgkmcnt(1)
	v_mfma_f32_16x16x32_bf16 v[76:79], v[152:155], v[228:231], v[76:79]
	v_mfma_f32_16x16x32_bf16 v[68:71], v[160:163], v[228:231], v[68:71]
	v_mfma_f32_16x16x32_bf16 v[148:151], v[156:159], v[194:197], v[148:151]
	v_mfma_f32_16x16x32_bf16 v[140:143], v[170:173], v[194:197], v[140:143]
	v_mfma_f32_16x16x32_bf16 v[132:135], v[156:159], v[202:205], v[132:135]
	v_mfma_f32_16x16x32_bf16 v[124:127], v[170:173], v[202:205], v[124:127]
	v_mfma_f32_16x16x32_bf16 v[116:119], v[156:159], v[224:227], v[116:119]
	v_mfma_f32_16x16x32_bf16 v[108:111], v[170:173], v[224:227], v[108:111]
	s_waitcnt lgkmcnt(0)
	v_mfma_f32_16x16x32_bf16 v[76:79], v[156:159], v[240:243], v[76:79]
	v_mfma_f32_16x16x32_bf16 v[68:71], v[170:173], v[240:243], v[68:71]
	v_mfma_f32_16x16x32_bf16 v[144:147], v[174:177], v[190:193], v[144:147]
	v_mfma_f32_16x16x32_bf16 v[136:139], v[182:185], v[190:193], v[136:139]
	v_mfma_f32_16x16x32_bf16 v[128:131], v[174:177], v[198:201], v[128:131]
	v_mfma_f32_16x16x32_bf16 v[120:123], v[182:185], v[198:201], v[120:123]
	v_mfma_f32_16x16x32_bf16 v[112:115], v[174:177], v[220:223], v[112:115]
	v_mfma_f32_16x16x32_bf16 v[104:107], v[182:185], v[220:223], v[104:107]
	v_mfma_f32_16x16x32_bf16 v[72:75], v[174:177], v[228:231], v[72:75]
	v_mfma_f32_16x16x32_bf16 v[64:67], v[182:185], v[228:231], v[64:67]
	v_mfma_f32_16x16x32_bf16 v[144:147], v[178:181], v[194:197], v[144:147]
	v_mfma_f32_16x16x32_bf16 v[136:139], v[186:189], v[194:197], v[136:139]
	v_mfma_f32_16x16x32_bf16 v[128:131], v[178:181], v[202:205], v[128:131]
	v_mfma_f32_16x16x32_bf16 v[120:123], v[186:189], v[202:205], v[120:123]
	v_mfma_f32_16x16x32_bf16 v[112:115], v[178:181], v[224:227], v[112:115]
	v_mfma_f32_16x16x32_bf16 v[104:107], v[186:189], v[224:227], v[104:107]
	v_mfma_f32_16x16x32_bf16 v[72:75], v[178:181], v[240:243], v[72:75]
	v_mfma_f32_16x16x32_bf16 v[64:67], v[186:189], v[240:243], v[64:67]
	s_barrier
	ds_read_b128 v[190:193], v169 offset:16384
	ds_read_b128 v[194:197], v169 offset:17408
	ds_read_b128 v[198:201], v169 offset:18432
	ds_read_b128 v[202:205], v169 offset:19456
	ds_read_b128 v[220:223], v169 offset:20480
	ds_read_b128 v[224:227], v169 offset:21504
	ds_read_b128 v[228:231], v169 offset:22528
	ds_read_b128 v[240:243], v169 offset:23552
	s_mov_b32 m0, s7
	s_nop 0
	buffer_load_dwordx4 v166, s[28:31], s55 offen lds
	s_add_i32 s57, s55, 0x80000
	s_mov_b32 m0, s8
	s_nop 0
	buffer_load_dwordx4 v167, s[28:31], s55 offen lds
	s_nop 0
	s_mov_b32 m0, s9
	s_nop 0
	buffer_load_dwordx4 v166, s[28:31], s57 offen lds
	s_nop 0
	s_mov_b32 m0, s10
	s_nop 0
	buffer_load_dwordx4 v167, s[28:31], s57 offen lds
	s_nop 0
	s_mov_b32 m0, s6
	s_nop 0
	buffer_load_dwordx4 v166, s[24:27], s56 offen lds
	s_nop 0
	s_mov_b32 m0, s11
	s_nop 0
	buffer_load_dwordx4 v167, s[24:27], s56 offen lds
	s_waitcnt vmcnt(8)
	s_waitcnt lgkmcnt(0)
	s_barrier
	s_waitcnt lgkmcnt(7)
	v_mfma_f32_16x16x32_bf16 v[60:63], v[152:155], v[190:193], v[60:63]
	v_mfma_f32_16x16x32_bf16 v[52:55], v[160:163], v[190:193], v[52:55]
	s_waitcnt lgkmcnt(5)
	v_mfma_f32_16x16x32_bf16 v[44:47], v[152:155], v[198:201], v[44:47]
	v_mfma_f32_16x16x32_bf16 v[36:39], v[160:163], v[198:201], v[36:39]
	s_waitcnt lgkmcnt(3)
	v_mfma_f32_16x16x32_bf16 v[28:31], v[152:155], v[220:223], v[28:31]
	v_mfma_f32_16x16x32_bf16 v[20:23], v[160:163], v[220:223], v[20:23]
	s_waitcnt lgkmcnt(1)
	v_mfma_f32_16x16x32_bf16 v[12:15], v[152:155], v[228:231], v[12:15]
	v_mfma_f32_16x16x32_bf16 v[4:7], v[160:163], v[228:231], v[4:7]
	v_mfma_f32_16x16x32_bf16 v[60:63], v[156:159], v[194:197], v[60:63]
	v_mfma_f32_16x16x32_bf16 v[52:55], v[170:173], v[194:197], v[52:55]
	v_mfma_f32_16x16x32_bf16 v[44:47], v[156:159], v[202:205], v[44:47]
	v_mfma_f32_16x16x32_bf16 v[36:39], v[170:173], v[202:205], v[36:39]
	v_mfma_f32_16x16x32_bf16 v[28:31], v[156:159], v[224:227], v[28:31]
	v_mfma_f32_16x16x32_bf16 v[20:23], v[170:173], v[224:227], v[20:23]
	s_waitcnt lgkmcnt(0)
	v_mfma_f32_16x16x32_bf16 v[12:15], v[156:159], v[240:243], v[12:15]
	v_mfma_f32_16x16x32_bf16 v[4:7], v[170:173], v[240:243], v[4:7]
	v_mfma_f32_16x16x32_bf16 v[56:59], v[174:177], v[190:193], v[56:59]
	v_mfma_f32_16x16x32_bf16 v[48:51], v[182:185], v[190:193], v[48:51]
	v_mfma_f32_16x16x32_bf16 v[40:43], v[174:177], v[198:201], v[40:43]
	v_mfma_f32_16x16x32_bf16 v[32:35], v[182:185], v[198:201], v[32:35]
	v_mfma_f32_16x16x32_bf16 v[24:27], v[174:177], v[220:223], v[24:27]
	v_mfma_f32_16x16x32_bf16 v[16:19], v[182:185], v[220:223], v[16:19]
	v_mfma_f32_16x16x32_bf16 v[8:11], v[174:177], v[228:231], v[8:11]
	v_mfma_f32_16x16x32_bf16 v[0:3], v[182:185], v[228:231], v[0:3]
	v_mfma_f32_16x16x32_bf16 v[56:59], v[178:181], v[194:197], v[56:59]
	v_mfma_f32_16x16x32_bf16 v[48:51], v[186:189], v[194:197], v[48:51]
	v_mfma_f32_16x16x32_bf16 v[40:43], v[178:181], v[202:205], v[40:43]
	v_mfma_f32_16x16x32_bf16 v[32:35], v[186:189], v[202:205], v[32:35]
	v_mfma_f32_16x16x32_bf16 v[24:27], v[178:181], v[224:227], v[24:27]
	v_mfma_f32_16x16x32_bf16 v[16:19], v[186:189], v[224:227], v[16:19]
	v_mfma_f32_16x16x32_bf16 v[8:11], v[178:181], v[240:243], v[8:11]
	v_mfma_f32_16x16x32_bf16 v[0:3], v[186:189], v[240:243], v[0:3]
	s_barrier
	v_add_u32_e32 v164, 0x18000, v168
	ds_read_b128 v[152:155], v164
	ds_read_b128 v[156:159], v164 offset:1024
	ds_read_b128 v[160:163], v164 offset:2048
	ds_read_b128 v[170:173], v164 offset:3072
	v_add_u32_e32 v164, 0x1c000, v168
	ds_read_b128 v[174:177], v164
	ds_read_b128 v[178:181], v164 offset:1024
	ds_read_b128 v[182:185], v164 offset:2048
	ds_read_b128 v[186:189], v164 offset:3072
	ds_read_b128 v[190:193], v169 offset:32768
	ds_read_b128 v[194:197], v169 offset:33792
	ds_read_b128 v[198:201], v169 offset:34816
	ds_read_b128 v[202:205], v169 offset:35840
	ds_read_b128 v[220:223], v169 offset:36864
	ds_read_b128 v[224:227], v169 offset:37888
	ds_read_b128 v[228:231], v169 offset:38912
	ds_read_b128 v[240:243], v169 offset:39936
	s_add_i32 s56, s56, 0x80000
	s_mov_b32 m0, s12
	s_nop 0
	buffer_load_dwordx4 v166, s[24:27], s56 offen lds
	s_nop 0
	s_mov_b32 m0, s13
	s_nop 0
	buffer_load_dwordx4 v167, s[24:27], s56 offen lds
	s_waitcnt vmcnt(8)
	s_waitcnt lgkmcnt(0)
	s_barrier
	s_waitcnt lgkmcnt(7)
	v_mfma_f32_16x16x32_bf16 v[148:151], v[152:155], v[190:193], v[148:151]
	v_mfma_f32_16x16x32_bf16 v[140:143], v[160:163], v[190:193], v[140:143]
	s_waitcnt lgkmcnt(5)
	v_mfma_f32_16x16x32_bf16 v[132:135], v[152:155], v[198:201], v[132:135]
	v_mfma_f32_16x16x32_bf16 v[124:127], v[160:163], v[198:201], v[124:127]
	s_waitcnt lgkmcnt(3)
	v_mfma_f32_16x16x32_bf16 v[116:119], v[152:155], v[220:223], v[116:119]
	v_mfma_f32_16x16x32_bf16 v[108:111], v[160:163], v[220:223], v[108:111]
	s_waitcnt lgkmcnt(1)
	v_mfma_f32_16x16x32_bf16 v[76:79], v[152:155], v[228:231], v[76:79]
	v_mfma_f32_16x16x32_bf16 v[68:71], v[160:163], v[228:231], v[68:71]
	v_mfma_f32_16x16x32_bf16 v[148:151], v[156:159], v[194:197], v[148:151]
	v_mfma_f32_16x16x32_bf16 v[140:143], v[170:173], v[194:197], v[140:143]
	v_mfma_f32_16x16x32_bf16 v[132:135], v[156:159], v[202:205], v[132:135]
	v_mfma_f32_16x16x32_bf16 v[124:127], v[170:173], v[202:205], v[124:127]
	v_mfma_f32_16x16x32_bf16 v[116:119], v[156:159], v[224:227], v[116:119]
	v_mfma_f32_16x16x32_bf16 v[108:111], v[170:173], v[224:227], v[108:111]
	s_waitcnt lgkmcnt(0)
	v_mfma_f32_16x16x32_bf16 v[76:79], v[156:159], v[240:243], v[76:79]
	v_mfma_f32_16x16x32_bf16 v[68:71], v[170:173], v[240:243], v[68:71]
	v_mfma_f32_16x16x32_bf16 v[144:147], v[174:177], v[190:193], v[144:147]
	v_mfma_f32_16x16x32_bf16 v[136:139], v[182:185], v[190:193], v[136:139]
	v_mfma_f32_16x16x32_bf16 v[128:131], v[174:177], v[198:201], v[128:131]
	v_mfma_f32_16x16x32_bf16 v[120:123], v[182:185], v[198:201], v[120:123]
	v_mfma_f32_16x16x32_bf16 v[112:115], v[174:177], v[220:223], v[112:115]
	v_mfma_f32_16x16x32_bf16 v[104:107], v[182:185], v[220:223], v[104:107]
	v_mfma_f32_16x16x32_bf16 v[72:75], v[174:177], v[228:231], v[72:75]
	v_mfma_f32_16x16x32_bf16 v[64:67], v[182:185], v[228:231], v[64:67]
	v_mfma_f32_16x16x32_bf16 v[144:147], v[178:181], v[194:197], v[144:147]
	v_mfma_f32_16x16x32_bf16 v[136:139], v[186:189], v[194:197], v[136:139]
	v_mfma_f32_16x16x32_bf16 v[128:131], v[178:181], v[202:205], v[128:131]
	v_mfma_f32_16x16x32_bf16 v[120:123], v[186:189], v[202:205], v[120:123]
	v_mfma_f32_16x16x32_bf16 v[112:115], v[178:181], v[224:227], v[112:115]
	v_mfma_f32_16x16x32_bf16 v[104:107], v[186:189], v[224:227], v[104:107]
	v_mfma_f32_16x16x32_bf16 v[72:75], v[178:181], v[240:243], v[72:75]
	v_mfma_f32_16x16x32_bf16 v[64:67], v[186:189], v[240:243], v[64:67]
	s_barrier
	ds_read_b128 v[190:193], v169 offset:49152
	ds_read_b128 v[194:197], v169 offset:50176
	ds_read_b128 v[198:201], v169 offset:51200
	ds_read_b128 v[202:205], v169 offset:52224
	ds_read_b128 v[220:223], v169 offset:53248
	ds_read_b128 v[224:227], v169 offset:54272
	ds_read_b128 v[228:231], v169 offset:55296
	ds_read_b128 v[240:243], v169 offset:56320
	s_or_b32 s56, s55, 0x4000
	s_mov_b32 m0, s16
	s_nop 0
	buffer_load_dwordx4 v166, s[28:31], s56 offen lds
	s_add_i32 s55, s55, 0x84000
	s_mov_b32 m0, s17
	s_nop 0
	buffer_load_dwordx4 v167, s[28:31], s56 offen lds
	s_nop 0
	s_mov_b32 m0, s34
	s_nop 0
	buffer_load_dwordx4 v166, s[28:31], s55 offen lds
	s_nop 0
	s_mov_b32 m0, s40
	s_nop 0
	buffer_load_dwordx4 v167, s[28:31], s55 offen lds
	s_nop 0
	s_mov_b32 m0, s18
	s_nop 0
	buffer_load_dwordx4 v166, s[24:27], s53 offen lds
	s_nop 0
	s_mov_b32 m0, s19
	s_nop 0
	buffer_load_dwordx4 v167, s[24:27], s53 offen lds
	s_waitcnt vmcnt(8)
	s_waitcnt lgkmcnt(0)
	s_barrier
	s_waitcnt lgkmcnt(7)
	v_mfma_f32_16x16x32_bf16 v[60:63], v[152:155], v[190:193], v[60:63]
	v_mfma_f32_16x16x32_bf16 v[52:55], v[160:163], v[190:193], v[52:55]
	s_waitcnt lgkmcnt(5)
	v_mfma_f32_16x16x32_bf16 v[44:47], v[152:155], v[198:201], v[44:47]
	v_mfma_f32_16x16x32_bf16 v[36:39], v[160:163], v[198:201], v[36:39]
	s_waitcnt lgkmcnt(3)
	v_mfma_f32_16x16x32_bf16 v[28:31], v[152:155], v[220:223], v[28:31]
	v_mfma_f32_16x16x32_bf16 v[20:23], v[160:163], v[220:223], v[20:23]
	s_waitcnt lgkmcnt(1)
	v_mfma_f32_16x16x32_bf16 v[12:15], v[152:155], v[228:231], v[12:15]
	v_mfma_f32_16x16x32_bf16 v[4:7], v[160:163], v[228:231], v[4:7]
	v_mfma_f32_16x16x32_bf16 v[60:63], v[156:159], v[194:197], v[60:63]
	v_mfma_f32_16x16x32_bf16 v[52:55], v[170:173], v[194:197], v[52:55]
	v_mfma_f32_16x16x32_bf16 v[44:47], v[156:159], v[202:205], v[44:47]
	v_mfma_f32_16x16x32_bf16 v[36:39], v[170:173], v[202:205], v[36:39]
	v_mfma_f32_16x16x32_bf16 v[28:31], v[156:159], v[224:227], v[28:31]
	v_mfma_f32_16x16x32_bf16 v[20:23], v[170:173], v[224:227], v[20:23]
	s_waitcnt lgkmcnt(0)
	v_mfma_f32_16x16x32_bf16 v[12:15], v[156:159], v[240:243], v[12:15]
	v_mfma_f32_16x16x32_bf16 v[4:7], v[170:173], v[240:243], v[4:7]
	v_mfma_f32_16x16x32_bf16 v[56:59], v[174:177], v[190:193], v[56:59]
	v_mfma_f32_16x16x32_bf16 v[48:51], v[182:185], v[190:193], v[48:51]
	v_mfma_f32_16x16x32_bf16 v[40:43], v[174:177], v[198:201], v[40:43]
	v_mfma_f32_16x16x32_bf16 v[32:35], v[182:185], v[198:201], v[32:35]
	v_mfma_f32_16x16x32_bf16 v[24:27], v[174:177], v[220:223], v[24:27]
	v_mfma_f32_16x16x32_bf16 v[16:19], v[182:185], v[220:223], v[16:19]
	v_mfma_f32_16x16x32_bf16 v[8:11], v[174:177], v[228:231], v[8:11]
	v_mfma_f32_16x16x32_bf16 v[0:3], v[182:185], v[228:231], v[0:3]
	v_mfma_f32_16x16x32_bf16 v[56:59], v[178:181], v[194:197], v[56:59]
	v_mfma_f32_16x16x32_bf16 v[48:51], v[186:189], v[194:197], v[48:51]
	v_mfma_f32_16x16x32_bf16 v[40:43], v[178:181], v[202:205], v[40:43]
	v_mfma_f32_16x16x32_bf16 v[32:35], v[186:189], v[202:205], v[32:35]
	v_mfma_f32_16x16x32_bf16 v[24:27], v[178:181], v[224:227], v[24:27]
	v_mfma_f32_16x16x32_bf16 v[16:19], v[186:189], v[224:227], v[16:19]
	v_mfma_f32_16x16x32_bf16 v[8:11], v[178:181], v[240:243], v[8:11]
	v_mfma_f32_16x16x32_bf16 v[0:3], v[186:189], v[240:243], v[0:3]
	s_barrier
	s_add_i32 s52, s52, 2
	s_add_i32 s37, s37, 0x8000
	s_add_i32 s51, s51, 0x8000
	s_cmp_gt_u32 s52, 29
	s_cbranch_scc0 .LBB0_795

.Lnb_p6:
	s_add_i32 s11, s8, 0xffea4000
	s_cmpk_eq_i32 s10, 0x54
	s_cselect_b32 s13, s6, s11
	s_cselect_b32 s12, s7, s9
	s_or_b32 s11, s13, 0x4000
	s_mov_b32 m0, s87
	s_nop 0
	buffer_load_dwordx4 v220, s[20:23], s8 offen lds
	s_nop 0
	s_mov_b32 m0, s89
	s_nop 0
	buffer_load_dwordx4 v221, s[20:23], s8 offen lds
	s_waitcnt vmcnt(24)
	s_waitcnt lgkmcnt(0)
	s_barrier
	s_waitcnt lgkmcnt(7)
	v_mfma_f32_16x16x32_bf16 v[164:167], v[128:131], v[184:187], 0
	v_mfma_f32_16x16x32_bf16 v[160:163], v[152:155], v[184:187], 0
	s_waitcnt lgkmcnt(5)
	v_mfma_f32_16x16x32_bf16 v[136:139], v[128:131], v[192:195], 0
	v_mfma_f32_16x16x32_bf16 v[132:135], v[152:155], v[192:195], 0
	s_waitcnt lgkmcnt(3)
	v_mfma_f32_16x16x32_bf16 v[116:119], v[128:131], v[200:203], 0
	v_mfma_f32_16x16x32_bf16 v[112:115], v[152:155], v[200:203], 0
	s_waitcnt lgkmcnt(1)
	v_mfma_f32_16x16x32_bf16 v[76:79], v[128:131], v[224:227], 0
	v_mfma_f32_16x16x32_bf16 v[72:75], v[152:155], v[224:227], 0
	v_mfma_f32_16x16x32_bf16 v[164:167], v[140:143], v[188:191], v[164:167]
	v_mfma_f32_16x16x32_bf16 v[160:163], v[156:159], v[188:191], v[160:163]
	v_mfma_f32_16x16x32_bf16 v[136:139], v[140:143], v[196:199], v[136:139]
	v_mfma_f32_16x16x32_bf16 v[132:135], v[156:159], v[196:199], v[132:135]
	v_mfma_f32_16x16x32_bf16 v[116:119], v[140:143], v[204:207], v[116:119]
	v_mfma_f32_16x16x32_bf16 v[112:115], v[156:159], v[204:207], v[112:115]
	s_waitcnt lgkmcnt(0)
	v_mfma_f32_16x16x32_bf16 v[76:79], v[140:143], v[228:231], v[76:79]
	v_mfma_f32_16x16x32_bf16 v[72:75], v[156:159], v[228:231], v[72:75]
	v_mfma_f32_16x16x32_bf16 v[148:151], v[168:171], v[184:187], 0
	v_mfma_f32_16x16x32_bf16 v[144:147], v[176:179], v[184:187], 0
	v_mfma_f32_16x16x32_bf16 v[124:127], v[168:171], v[192:195], 0
	v_mfma_f32_16x16x32_bf16 v[120:123], v[176:179], v[192:195], 0
	v_mfma_f32_16x16x32_bf16 v[108:111], v[168:171], v[200:203], 0
	v_mfma_f32_16x16x32_bf16 v[104:107], v[176:179], v[200:203], 0
	v_mfma_f32_16x16x32_bf16 v[68:71], v[168:171], v[224:227], 0
	v_mfma_f32_16x16x32_bf16 v[64:67], v[176:179], v[224:227], 0
	v_mfma_f32_16x16x32_bf16 v[148:151], v[172:175], v[188:191], v[148:151]
	v_mfma_f32_16x16x32_bf16 v[144:147], v[180:183], v[188:191], v[144:147]
	v_mfma_f32_16x16x32_bf16 v[124:127], v[172:175], v[196:199], v[124:127]
	v_mfma_f32_16x16x32_bf16 v[120:123], v[180:183], v[196:199], v[120:123]
	v_mfma_f32_16x16x32_bf16 v[108:111], v[172:175], v[204:207], v[108:111]
	v_mfma_f32_16x16x32_bf16 v[104:107], v[180:183], v[204:207], v[104:107]
	v_mfma_f32_16x16x32_bf16 v[68:71], v[172:175], v[228:231], v[68:71]
	v_mfma_f32_16x16x32_bf16 v[64:67], v[180:183], v[228:231], v[64:67]
	s_barrier
	ds_read_b128 v[184:187], v223 offset:16384
	ds_read_b128 v[188:191], v223 offset:17408
	ds_read_b128 v[192:195], v223 offset:18432
	ds_read_b128 v[196:199], v223 offset:19456
	ds_read_b128 v[200:203], v223 offset:20480
	ds_read_b128 v[204:207], v223 offset:21504
	ds_read_b128 v[224:227], v223 offset:22528
	ds_read_b128 v[228:231], v223 offset:23552
	s_mov_b32 m0, s51
	s_nop 0
	buffer_load_dwordx4 v220, s[52:55], s12 offen lds
	s_add_i32 s14, s12, 0x160000
	s_mov_b32 m0, s74
	s_nop 0
	buffer_load_dwordx4 v221, s[52:55], s12 offen lds
	s_nop 0
	s_mov_b32 m0, s75
	s_nop 0
	buffer_load_dwordx4 v220, s[52:55], s14 offen lds
	s_nop 0
	s_mov_b32 m0, s76
	s_nop 0
	buffer_load_dwordx4 v221, s[52:55], s14 offen lds
	s_nop 0
	s_mov_b32 m0, s31
	s_nop 0
	buffer_load_dwordx4 v220, s[20:23], s13 offen lds
	s_nop 0
	s_mov_b32 m0, s77
	s_nop 0
	buffer_load_dwordx4 v221, s[20:23], s13 offen lds
	s_waitcnt vmcnt(24)
	s_waitcnt lgkmcnt(0)
	s_barrier
	s_waitcnt lgkmcnt(7)
	v_mfma_f32_16x16x32_bf16 v[60:63], v[128:131], v[184:187], 0
	v_mfma_f32_16x16x32_bf16 v[56:59], v[152:155], v[184:187], 0
	s_waitcnt lgkmcnt(5)
	v_mfma_f32_16x16x32_bf16 v[44:47], v[128:131], v[192:195], 0
	v_mfma_f32_16x16x32_bf16 v[40:43], v[152:155], v[192:195], 0
	s_waitcnt lgkmcnt(3)
	v_mfma_f32_16x16x32_bf16 v[28:31], v[128:131], v[200:203], 0
	v_mfma_f32_16x16x32_bf16 v[24:27], v[152:155], v[200:203], 0
	s_waitcnt lgkmcnt(1)
	v_mfma_f32_16x16x32_bf16 v[12:15], v[128:131], v[224:227], 0
	v_mfma_f32_16x16x32_bf16 v[8:11], v[152:155], v[224:227], 0
	v_mfma_f32_16x16x32_bf16 v[60:63], v[140:143], v[188:191], v[60:63]
	v_mfma_f32_16x16x32_bf16 v[56:59], v[156:159], v[188:191], v[56:59]
	v_mfma_f32_16x16x32_bf16 v[44:47], v[140:143], v[196:199], v[44:47]
	v_mfma_f32_16x16x32_bf16 v[40:43], v[156:159], v[196:199], v[40:43]
	v_mfma_f32_16x16x32_bf16 v[28:31], v[140:143], v[204:207], v[28:31]
	v_mfma_f32_16x16x32_bf16 v[24:27], v[156:159], v[204:207], v[24:27]
	s_waitcnt lgkmcnt(0)
	v_mfma_f32_16x16x32_bf16 v[12:15], v[140:143], v[228:231], v[12:15]
	v_mfma_f32_16x16x32_bf16 v[8:11], v[156:159], v[228:231], v[8:11]
	v_mfma_f32_16x16x32_bf16 v[52:55], v[168:171], v[184:187], 0
	v_mfma_f32_16x16x32_bf16 v[48:51], v[176:179], v[184:187], 0
	v_mfma_f32_16x16x32_bf16 v[36:39], v[168:171], v[192:195], 0
	v_mfma_f32_16x16x32_bf16 v[32:35], v[176:179], v[192:195], 0
	v_mfma_f32_16x16x32_bf16 v[20:23], v[168:171], v[200:203], 0
	v_mfma_f32_16x16x32_bf16 v[16:19], v[176:179], v[200:203], 0
	v_mfma_f32_16x16x32_bf16 v[4:7], v[168:171], v[224:227], 0
	v_mfma_f32_16x16x32_bf16 v[0:3], v[176:179], v[224:227], 0
	v_mfma_f32_16x16x32_bf16 v[52:55], v[172:175], v[188:191], v[52:55]
	v_mfma_f32_16x16x32_bf16 v[48:51], v[180:183], v[188:191], v[48:51]
	v_mfma_f32_16x16x32_bf16 v[36:39], v[172:175], v[196:199], v[36:39]
	v_mfma_f32_16x16x32_bf16 v[32:35], v[180:183], v[196:199], v[32:35]
	v_mfma_f32_16x16x32_bf16 v[20:23], v[172:175], v[204:207], v[20:23]
	v_mfma_f32_16x16x32_bf16 v[16:19], v[180:183], v[204:207], v[16:19]
	v_mfma_f32_16x16x32_bf16 v[4:7], v[172:175], v[228:231], v[4:7]
	v_mfma_f32_16x16x32_bf16 v[0:3], v[180:183], v[228:231], v[0:3]
	s_barrier
	v_add_u32_e32 v156, 0x18000, v222
	v_add_u32_e32 v180, 0x1c000, v222
	ds_read_b128 v[128:131], v156
	ds_read_b128 v[140:143], v156 offset:1024
	ds_read_b128 v[152:155], v156 offset:2048
	ds_read_b128 v[156:159], v156 offset:3072
	ds_read_b128 v[168:171], v180
	ds_read_b128 v[172:175], v180 offset:1024
	ds_read_b128 v[176:179], v180 offset:2048
	ds_read_b128 v[180:183], v180 offset:3072
	ds_read_b128 v[184:187], v223 offset:32768
	ds_read_b128 v[188:191], v223 offset:33792
	ds_read_b128 v[192:195], v223 offset:34816
	ds_read_b128 v[196:199], v223 offset:35840
	ds_read_b128 v[200:203], v223 offset:36864
	ds_read_b128 v[204:207], v223 offset:37888
	ds_read_b128 v[224:227], v223 offset:38912
	ds_read_b128 v[228:231], v223 offset:39936
	s_add_i32 s13, s13, 0x160000
	s_mov_b32 m0, s78
	s_nop 0
	buffer_load_dwordx4 v220, s[20:23], s13 offen lds
	s_nop 0
	s_mov_b32 m0, s79
	s_nop 0
	buffer_load_dwordx4 v221, s[20:23], s13 offen lds
	s_waitcnt vmcnt(8)
	s_waitcnt lgkmcnt(0)
	s_barrier
	s_waitcnt lgkmcnt(7)
	v_mfma_f32_16x16x32_bf16 v[164:167], v[128:131], v[184:187], v[164:167]
	v_mfma_f32_16x16x32_bf16 v[160:163], v[152:155], v[184:187], v[160:163]
	s_waitcnt lgkmcnt(5)
	v_mfma_f32_16x16x32_bf16 v[136:139], v[128:131], v[192:195], v[136:139]
	v_mfma_f32_16x16x32_bf16 v[132:135], v[152:155], v[192:195], v[132:135]
	s_waitcnt lgkmcnt(3)
	v_mfma_f32_16x16x32_bf16 v[116:119], v[128:131], v[200:203], v[116:119]
	v_mfma_f32_16x16x32_bf16 v[112:115], v[152:155], v[200:203], v[112:115]
	s_waitcnt lgkmcnt(1)
	v_mfma_f32_16x16x32_bf16 v[76:79], v[128:131], v[224:227], v[76:79]
	v_mfma_f32_16x16x32_bf16 v[72:75], v[152:155], v[224:227], v[72:75]
	v_mfma_f32_16x16x32_bf16 v[164:167], v[140:143], v[188:191], v[164:167]
	v_mfma_f32_16x16x32_bf16 v[160:163], v[156:159], v[188:191], v[160:163]
	v_mfma_f32_16x16x32_bf16 v[136:139], v[140:143], v[196:199], v[136:139]
	v_mfma_f32_16x16x32_bf16 v[132:135], v[156:159], v[196:199], v[132:135]
	v_mfma_f32_16x16x32_bf16 v[116:119], v[140:143], v[204:207], v[116:119]
	v_mfma_f32_16x16x32_bf16 v[112:115], v[156:159], v[204:207], v[112:115]
	s_waitcnt lgkmcnt(0)
	v_mfma_f32_16x16x32_bf16 v[76:79], v[140:143], v[228:231], v[76:79]
	v_mfma_f32_16x16x32_bf16 v[72:75], v[156:159], v[228:231], v[72:75]
	v_mfma_f32_16x16x32_bf16 v[148:151], v[168:171], v[184:187], v[148:151]
	v_mfma_f32_16x16x32_bf16 v[144:147], v[176:179], v[184:187], v[144:147]
	v_mfma_f32_16x16x32_bf16 v[124:127], v[168:171], v[192:195], v[124:127]
	v_mfma_f32_16x16x32_bf16 v[120:123], v[176:179], v[192:195], v[120:123]
	v_mfma_f32_16x16x32_bf16 v[108:111], v[168:171], v[200:203], v[108:111]
	v_mfma_f32_16x16x32_bf16 v[104:107], v[176:179], v[200:203], v[104:107]
	v_mfma_f32_16x16x32_bf16 v[68:71], v[168:171], v[224:227], v[68:71]
	v_mfma_f32_16x16x32_bf16 v[64:67], v[176:179], v[224:227], v[64:67]
	v_mfma_f32_16x16x32_bf16 v[148:151], v[172:175], v[188:191], v[148:151]
	v_mfma_f32_16x16x32_bf16 v[144:147], v[180:183], v[188:191], v[144:147]
	v_mfma_f32_16x16x32_bf16 v[124:127], v[172:175], v[196:199], v[124:127]
	v_mfma_f32_16x16x32_bf16 v[120:123], v[180:183], v[196:199], v[120:123]
	v_mfma_f32_16x16x32_bf16 v[108:111], v[172:175], v[204:207], v[108:111]
	v_mfma_f32_16x16x32_bf16 v[104:107], v[180:183], v[204:207], v[104:107]
	v_mfma_f32_16x16x32_bf16 v[68:71], v[172:175], v[228:231], v[68:71]
	v_mfma_f32_16x16x32_bf16 v[64:67], v[180:183], v[228:231], v[64:67]
	s_barrier
	ds_read_b128 v[184:187], v223 offset:49152
	ds_read_b128 v[188:191], v223 offset:50176
	ds_read_b128 v[192:195], v223 offset:51200
	ds_read_b128 v[196:199], v223 offset:52224
	ds_read_b128 v[200:203], v223 offset:53248
	ds_read_b128 v[204:207], v223 offset:54272
	ds_read_b128 v[224:227], v223 offset:55296
	ds_read_b128 v[228:231], v223 offset:56320
	s_or_b32 s13, s12, 0x4000
	s_mov_b32 m0, s34
	s_nop 0
	buffer_load_dwordx4 v220, s[52:55], s13 offen lds
	s_add_i32 s12, s12, 0x164000
	s_mov_b32 m0, s82
	s_nop 0
	buffer_load_dwordx4 v221, s[52:55], s13 offen lds
	s_nop 0
	s_mov_b32 m0, s85
	s_nop 0
	buffer_load_dwordx4 v220, s[52:55], s12 offen lds
	s_nop 0
	s_mov_b32 m0, s86
	s_nop 0
	buffer_load_dwordx4 v221, s[52:55], s12 offen lds
	s_nop 0
	s_mov_b32 m0, s83
	s_nop 0
	buffer_load_dwordx4 v220, s[20:23], s11 offen lds
	s_nop 0
	s_mov_b32 m0, s84
	s_nop 0
	buffer_load_dwordx4 v221, s[20:23], s11 offen lds
	s_waitcnt vmcnt(8)
	s_waitcnt lgkmcnt(0)
	s_barrier
	s_waitcnt lgkmcnt(7)
	v_mfma_f32_16x16x32_bf16 v[60:63], v[128:131], v[184:187], v[60:63]
	v_mfma_f32_16x16x32_bf16 v[56:59], v[152:155], v[184:187], v[56:59]
	s_waitcnt lgkmcnt(5)
	v_mfma_f32_16x16x32_bf16 v[44:47], v[128:131], v[192:195], v[44:47]
	v_mfma_f32_16x16x32_bf16 v[40:43], v[152:155], v[192:195], v[40:43]
	s_waitcnt lgkmcnt(3)
	v_mfma_f32_16x16x32_bf16 v[28:31], v[128:131], v[200:203], v[28:31]
	v_mfma_f32_16x16x32_bf16 v[24:27], v[152:155], v[200:203], v[24:27]
	s_waitcnt lgkmcnt(1)
	v_mfma_f32_16x16x32_bf16 v[12:15], v[128:131], v[224:227], v[12:15]
	v_mfma_f32_16x16x32_bf16 v[8:11], v[152:155], v[224:227], v[8:11]
	v_mfma_f32_16x16x32_bf16 v[60:63], v[140:143], v[188:191], v[60:63]
	v_mfma_f32_16x16x32_bf16 v[56:59], v[156:159], v[188:191], v[56:59]
	v_mfma_f32_16x16x32_bf16 v[44:47], v[140:143], v[196:199], v[44:47]
	v_mfma_f32_16x16x32_bf16 v[40:43], v[156:159], v[196:199], v[40:43]
	v_mfma_f32_16x16x32_bf16 v[28:31], v[140:143], v[204:207], v[28:31]
	v_mfma_f32_16x16x32_bf16 v[24:27], v[156:159], v[204:207], v[24:27]
	s_waitcnt lgkmcnt(0)
	v_mfma_f32_16x16x32_bf16 v[12:15], v[140:143], v[228:231], v[12:15]
	v_mfma_f32_16x16x32_bf16 v[8:11], v[156:159], v[228:231], v[8:11]
	v_mfma_f32_16x16x32_bf16 v[52:55], v[168:171], v[184:187], v[52:55]
	v_mfma_f32_16x16x32_bf16 v[48:51], v[176:179], v[184:187], v[48:51]
	v_mfma_f32_16x16x32_bf16 v[36:39], v[168:171], v[192:195], v[36:39]
	v_mfma_f32_16x16x32_bf16 v[32:35], v[176:179], v[192:195], v[32:35]
	v_mfma_f32_16x16x32_bf16 v[20:23], v[168:171], v[200:203], v[20:23]
	v_mfma_f32_16x16x32_bf16 v[16:19], v[176:179], v[200:203], v[16:19]
	v_mfma_f32_16x16x32_bf16 v[4:7], v[168:171], v[224:227], v[4:7]
	v_mfma_f32_16x16x32_bf16 v[0:3], v[176:179], v[224:227], v[0:3]
	v_mfma_f32_16x16x32_bf16 v[52:55], v[172:175], v[188:191], v[52:55]
	v_mfma_f32_16x16x32_bf16 v[48:51], v[180:183], v[188:191], v[48:51]
	v_mfma_f32_16x16x32_bf16 v[36:39], v[172:175], v[196:199], v[36:39]
	v_mfma_f32_16x16x32_bf16 v[32:35], v[180:183], v[196:199], v[32:35]
	v_mfma_f32_16x16x32_bf16 v[20:23], v[172:175], v[204:207], v[20:23]
	v_mfma_f32_16x16x32_bf16 v[16:19], v[180:183], v[204:207], v[16:19]
	v_mfma_f32_16x16x32_bf16 v[4:7], v[172:175], v[228:231], v[4:7]
	v_mfma_f32_16x16x32_bf16 v[0:3], v[180:183], v[228:231], v[0:3]
	s_barrier
	s_add_i32 s10, s10, 2
	s_add_i32 s8, s8, 0x8000
	s_add_i32 s9, s9, 0x8000
.LBB0_885:
	v_add_u32_e32 v156, 0x10000, v222
	v_add_u32_e32 v180, 0x14000, v222
	ds_read_b128 v[128:131], v156
	ds_read_b128 v[140:143], v156 offset:1024
	ds_read_b128 v[152:155], v156 offset:2048
	ds_read_b128 v[156:159], v156 offset:3072
	ds_read_b128 v[168:171], v180
	ds_read_b128 v[172:175], v180 offset:1024
	ds_read_b128 v[176:179], v180 offset:2048
	ds_read_b128 v[180:183], v180 offset:3072
	s_add_i32 s11, s8, 0xffea4000
	s_cmpk_eq_i32 s10, 0x54
	s_cselect_b32 s13, s6, s11
	s_cselect_b32 s12, s7, s9
	s_or_b32 s11, s13, 0x4000
	ds_read_b128 v[184:187], v223
	ds_read_b128 v[188:191], v223 offset:1024
	ds_read_b128 v[192:195], v223 offset:2048
	ds_read_b128 v[196:199], v223 offset:3072
	ds_read_b128 v[200:203], v223 offset:4096
	ds_read_b128 v[204:207], v223 offset:5120
	ds_read_b128 v[224:227], v223 offset:6144
	ds_read_b128 v[228:231], v223 offset:7168
	s_mov_b32 m0, s87
	s_nop 0
	buffer_load_dwordx4 v220, s[20:23], s8 offen lds
	s_nop 0
	s_mov_b32 m0, s89
	s_nop 0
	buffer_load_dwordx4 v221, s[20:23], s8 offen lds
	s_waitcnt vmcnt(8)
	s_waitcnt lgkmcnt(0)
	s_barrier
	s_waitcnt lgkmcnt(7)
	v_mfma_f32_16x16x32_bf16 v[164:167], v[128:131], v[184:187], v[164:167]
	v_mfma_f32_16x16x32_bf16 v[160:163], v[152:155], v[184:187], v[160:163]
	s_waitcnt lgkmcnt(5)
	v_mfma_f32_16x16x32_bf16 v[136:139], v[128:131], v[192:195], v[136:139]
	v_mfma_f32_16x16x32_bf16 v[132:135], v[152:155], v[192:195], v[132:135]
	s_waitcnt lgkmcnt(3)
	v_mfma_f32_16x16x32_bf16 v[116:119], v[128:131], v[200:203], v[116:119]
	v_mfma_f32_16x16x32_bf16 v[112:115], v[152:155], v[200:203], v[112:115]
	s_waitcnt lgkmcnt(1)
	v_mfma_f32_16x16x32_bf16 v[76:79], v[128:131], v[224:227], v[76:79]
	v_mfma_f32_16x16x32_bf16 v[72:75], v[152:155], v[224:227], v[72:75]
	v_mfma_f32_16x16x32_bf16 v[164:167], v[140:143], v[188:191], v[164:167]
	v_mfma_f32_16x16x32_bf16 v[160:163], v[156:159], v[188:191], v[160:163]
	v_mfma_f32_16x16x32_bf16 v[136:139], v[140:143], v[196:199], v[136:139]
	v_mfma_f32_16x16x32_bf16 v[132:135], v[156:159], v[196:199], v[132:135]
	v_mfma_f32_16x16x32_bf16 v[116:119], v[140:143], v[204:207], v[116:119]
	v_mfma_f32_16x16x32_bf16 v[112:115], v[156:159], v[204:207], v[112:115]
	s_waitcnt lgkmcnt(0)
	v_mfma_f32_16x16x32_bf16 v[76:79], v[140:143], v[228:231], v[76:79]
	v_mfma_f32_16x16x32_bf16 v[72:75], v[156:159], v[228:231], v[72:75]
	v_mfma_f32_16x16x32_bf16 v[148:151], v[168:171], v[184:187], v[148:151]
	v_mfma_f32_16x16x32_bf16 v[144:147], v[176:179], v[184:187], v[144:147]
	v_mfma_f32_16x16x32_bf16 v[124:127], v[168:171], v[192:195], v[124:127]
	v_mfma_f32_16x16x32_bf16 v[120:123], v[176:179], v[192:195], v[120:123]
	v_mfma_f32_16x16x32_bf16 v[108:111], v[168:171], v[200:203], v[108:111]
	v_mfma_f32_16x16x32_bf16 v[104:107], v[176:179], v[200:203], v[104:107]
	v_mfma_f32_16x16x32_bf16 v[68:71], v[168:171], v[224:227], v[68:71]
	v_mfma_f32_16x16x32_bf16 v[64:67], v[176:179], v[224:227], v[64:67]
	v_mfma_f32_16x16x32_bf16 v[148:151], v[172:175], v[188:191], v[148:151]
	v_mfma_f32_16x16x32_bf16 v[144:147], v[180:183], v[188:191], v[144:147]
	v_mfma_f32_16x16x32_bf16 v[124:127], v[172:175], v[196:199], v[124:127]
	v_mfma_f32_16x16x32_bf16 v[120:123], v[180:183], v[196:199], v[120:123]
	v_mfma_f32_16x16x32_bf16 v[108:111], v[172:175], v[204:207], v[108:111]
	v_mfma_f32_16x16x32_bf16 v[104:107], v[180:183], v[204:207], v[104:107]
	v_mfma_f32_16x16x32_bf16 v[68:71], v[172:175], v[228:231], v[68:71]
	v_mfma_f32_16x16x32_bf16 v[64:67], v[180:183], v[228:231], v[64:67]
	s_barrier
	ds_read_b128 v[184:187], v223 offset:16384
	ds_read_b128 v[188:191], v223 offset:17408
	ds_read_b128 v[192:195], v223 offset:18432
	ds_read_b128 v[196:199], v223 offset:19456
	ds_read_b128 v[200:203], v223 offset:20480
	ds_read_b128 v[204:207], v223 offset:21504
	ds_read_b128 v[224:227], v223 offset:22528
	ds_read_b128 v[228:231], v223 offset:23552
	s_mov_b32 m0, s51
	s_nop 0
	buffer_load_dwordx4 v220, s[52:55], s12 offen lds
	s_add_i32 s14, s12, 0x160000
	s_mov_b32 m0, s74
	s_nop 0
	buffer_load_dwordx4 v221, s[52:55], s12 offen lds
	s_nop 0
	s_mov_b32 m0, s75
	s_nop 0
	buffer_load_dwordx4 v220, s[52:55], s14 offen lds
	s_nop 0
	s_mov_b32 m0, s76
	s_nop 0
	buffer_load_dwordx4 v221, s[52:55], s14 offen lds
	s_nop 0
	s_mov_b32 m0, s31
	s_nop 0
	buffer_load_dwordx4 v220, s[20:23], s13 offen lds
	s_nop 0
	s_mov_b32 m0, s77
	s_nop 0
	buffer_load_dwordx4 v221, s[20:23], s13 offen lds
	s_waitcnt vmcnt(8)
	s_waitcnt lgkmcnt(0)
	s_barrier
	s_waitcnt lgkmcnt(7)
	v_mfma_f32_16x16x32_bf16 v[60:63], v[128:131], v[184:187], v[60:63]
	v_mfma_f32_16x16x32_bf16 v[56:59], v[152:155], v[184:187], v[56:59]
	s_waitcnt lgkmcnt(5)
	v_mfma_f32_16x16x32_bf16 v[44:47], v[128:131], v[192:195], v[44:47]
	v_mfma_f32_16x16x32_bf16 v[40:43], v[152:155], v[192:195], v[40:43]
	s_waitcnt lgkmcnt(3)
	v_mfma_f32_16x16x32_bf16 v[28:31], v[128:131], v[200:203], v[28:31]
	v_mfma_f32_16x16x32_bf16 v[24:27], v[152:155], v[200:203], v[24:27]
	s_waitcnt lgkmcnt(1)
	v_mfma_f32_16x16x32_bf16 v[12:15], v[128:131], v[224:227], v[12:15]
	v_mfma_f32_16x16x32_bf16 v[8:11], v[152:155], v[224:227], v[8:11]
	v_mfma_f32_16x16x32_bf16 v[60:63], v[140:143], v[188:191], v[60:63]
	v_mfma_f32_16x16x32_bf16 v[56:59], v[156:159], v[188:191], v[56:59]
	v_mfma_f32_16x16x32_bf16 v[44:47], v[140:143], v[196:199], v[44:47]
	v_mfma_f32_16x16x32_bf16 v[40:43], v[156:159], v[196:199], v[40:43]
	v_mfma_f32_16x16x32_bf16 v[28:31], v[140:143], v[204:207], v[28:31]
	v_mfma_f32_16x16x32_bf16 v[24:27], v[156:159], v[204:207], v[24:27]
	s_waitcnt lgkmcnt(0)
	v_mfma_f32_16x16x32_bf16 v[12:15], v[140:143], v[228:231], v[12:15]
	v_mfma_f32_16x16x32_bf16 v[8:11], v[156:159], v[228:231], v[8:11]
	v_mfma_f32_16x16x32_bf16 v[52:55], v[168:171], v[184:187], v[52:55]
	v_mfma_f32_16x16x32_bf16 v[48:51], v[176:179], v[184:187], v[48:51]
	v_mfma_f32_16x16x32_bf16 v[36:39], v[168:171], v[192:195], v[36:39]
	v_mfma_f32_16x16x32_bf16 v[32:35], v[176:179], v[192:195], v[32:35]
	v_mfma_f32_16x16x32_bf16 v[20:23], v[168:171], v[200:203], v[20:23]
	v_mfma_f32_16x16x32_bf16 v[16:19], v[176:179], v[200:203], v[16:19]
	v_mfma_f32_16x16x32_bf16 v[4:7], v[168:171], v[224:227], v[4:7]
	v_mfma_f32_16x16x32_bf16 v[0:3], v[176:179], v[224:227], v[0:3]
	v_mfma_f32_16x16x32_bf16 v[52:55], v[172:175], v[188:191], v[52:55]
	v_mfma_f32_16x16x32_bf16 v[48:51], v[180:183], v[188:191], v[48:51]
	v_mfma_f32_16x16x32_bf16 v[36:39], v[172:175], v[196:199], v[36:39]
	v_mfma_f32_16x16x32_bf16 v[32:35], v[180:183], v[196:199], v[32:35]
	v_mfma_f32_16x16x32_bf16 v[20:23], v[172:175], v[204:207], v[20:23]
	v_mfma_f32_16x16x32_bf16 v[16:19], v[180:183], v[204:207], v[16:19]
	v_mfma_f32_16x16x32_bf16 v[4:7], v[172:175], v[228:231], v[4:7]
	v_mfma_f32_16x16x32_bf16 v[0:3], v[180:183], v[228:231], v[0:3]
	s_barrier
	v_add_u32_e32 v156, 0x18000, v222
	v_add_u32_e32 v180, 0x1c000, v222
	ds_read_b128 v[128:131], v156
	ds_read_b128 v[140:143], v156 offset:1024
	ds_read_b128 v[152:155], v156 offset:2048
	ds_read_b128 v[156:159], v156 offset:3072
	ds_read_b128 v[168:171], v180
	ds_read_b128 v[172:175], v180 offset:1024
	ds_read_b128 v[176:179], v180 offset:2048
	ds_read_b128 v[180:183], v180 offset:3072
	ds_read_b128 v[184:187], v223 offset:32768
	ds_read_b128 v[188:191], v223 offset:33792
	ds_read_b128 v[192:195], v223 offset:34816
	ds_read_b128 v[196:199], v223 offset:35840
	ds_read_b128 v[200:203], v223 offset:36864
	ds_read_b128 v[204:207], v223 offset:37888
	ds_read_b128 v[224:227], v223 offset:38912
	ds_read_b128 v[228:231], v223 offset:39936
	s_add_i32 s13, s13, 0x160000
	s_mov_b32 m0, s78
	s_nop 0
	buffer_load_dwordx4 v220, s[20:23], s13 offen lds
	s_nop 0
	s_mov_b32 m0, s79
	s_nop 0
	buffer_load_dwordx4 v221, s[20:23], s13 offen lds
	s_waitcnt vmcnt(8)
	s_waitcnt lgkmcnt(0)
	s_barrier
	s_waitcnt lgkmcnt(7)
	v_mfma_f32_16x16x32_bf16 v[164:167], v[128:131], v[184:187], v[164:167]
	v_mfma_f32_16x16x32_bf16 v[160:163], v[152:155], v[184:187], v[160:163]
	s_waitcnt lgkmcnt(5)
	v_mfma_f32_16x16x32_bf16 v[136:139], v[128:131], v[192:195], v[136:139]
	v_mfma_f32_16x16x32_bf16 v[132:135], v[152:155], v[192:195], v[132:135]
	s_waitcnt lgkmcnt(3)
	v_mfma_f32_16x16x32_bf16 v[116:119], v[128:131], v[200:203], v[116:119]
	v_mfma_f32_16x16x32_bf16 v[112:115], v[152:155], v[200:203], v[112:115]
	s_waitcnt lgkmcnt(1)
	v_mfma_f32_16x16x32_bf16 v[76:79], v[128:131], v[224:227], v[76:79]
	v_mfma_f32_16x16x32_bf16 v[72:75], v[152:155], v[224:227], v[72:75]
	v_mfma_f32_16x16x32_bf16 v[164:167], v[140:143], v[188:191], v[164:167]
	v_mfma_f32_16x16x32_bf16 v[160:163], v[156:159], v[188:191], v[160:163]
	v_mfma_f32_16x16x32_bf16 v[136:139], v[140:143], v[196:199], v[136:139]
	v_mfma_f32_16x16x32_bf16 v[132:135], v[156:159], v[196:199], v[132:135]
	v_mfma_f32_16x16x32_bf16 v[116:119], v[140:143], v[204:207], v[116:119]
	v_mfma_f32_16x16x32_bf16 v[112:115], v[156:159], v[204:207], v[112:115]
	s_waitcnt lgkmcnt(0)
	v_mfma_f32_16x16x32_bf16 v[76:79], v[140:143], v[228:231], v[76:79]
	v_mfma_f32_16x16x32_bf16 v[72:75], v[156:159], v[228:231], v[72:75]
	v_mfma_f32_16x16x32_bf16 v[148:151], v[168:171], v[184:187], v[148:151]
	v_mfma_f32_16x16x32_bf16 v[144:147], v[176:179], v[184:187], v[144:147]
	v_mfma_f32_16x16x32_bf16 v[124:127], v[168:171], v[192:195], v[124:127]
	v_mfma_f32_16x16x32_bf16 v[120:123], v[176:179], v[192:195], v[120:123]
	v_mfma_f32_16x16x32_bf16 v[108:111], v[168:171], v[200:203], v[108:111]
	v_mfma_f32_16x16x32_bf16 v[104:107], v[176:179], v[200:203], v[104:107]
	v_mfma_f32_16x16x32_bf16 v[68:71], v[168:171], v[224:227], v[68:71]
	v_mfma_f32_16x16x32_bf16 v[64:67], v[176:179], v[224:227], v[64:67]
	v_mfma_f32_16x16x32_bf16 v[148:151], v[172:175], v[188:191], v[148:151]
	v_mfma_f32_16x16x32_bf16 v[144:147], v[180:183], v[188:191], v[144:147]
	v_mfma_f32_16x16x32_bf16 v[124:127], v[172:175], v[196:199], v[124:127]
	v_mfma_f32_16x16x32_bf16 v[120:123], v[180:183], v[196:199], v[120:123]
	v_mfma_f32_16x16x32_bf16 v[108:111], v[172:175], v[204:207], v[108:111]
	v_mfma_f32_16x16x32_bf16 v[104:107], v[180:183], v[204:207], v[104:107]
	v_mfma_f32_16x16x32_bf16 v[68:71], v[172:175], v[228:231], v[68:71]
	v_mfma_f32_16x16x32_bf16 v[64:67], v[180:183], v[228:231], v[64:67]
	s_barrier
	ds_read_b128 v[184:187], v223 offset:49152
	ds_read_b128 v[188:191], v223 offset:50176
	ds_read_b128 v[192:195], v223 offset:51200
	ds_read_b128 v[196:199], v223 offset:52224
	ds_read_b128 v[200:203], v223 offset:53248
	ds_read_b128 v[204:207], v223 offset:54272
	ds_read_b128 v[224:227], v223 offset:55296
	ds_read_b128 v[228:231], v223 offset:56320
	s_or_b32 s13, s12, 0x4000
	s_mov_b32 m0, s34
	s_nop 0
	buffer_load_dwordx4 v220, s[52:55], s13 offen lds
	s_add_i32 s12, s12, 0x164000
	s_mov_b32 m0, s82
	s_nop 0
	buffer_load_dwordx4 v221, s[52:55], s13 offen lds
	s_nop 0
	s_mov_b32 m0, s85
	s_nop 0
	buffer_load_dwordx4 v220, s[52:55], s12 offen lds
	s_nop 0
	s_mov_b32 m0, s86
	s_nop 0
	buffer_load_dwordx4 v221, s[52:55], s12 offen lds
	s_nop 0
	s_mov_b32 m0, s83
	s_nop 0
	buffer_load_dwordx4 v220, s[20:23], s11 offen lds
	s_nop 0
	s_mov_b32 m0, s84
	s_nop 0
	buffer_load_dwordx4 v221, s[20:23], s11 offen lds
	s_waitcnt vmcnt(8)
	s_waitcnt lgkmcnt(0)
	s_barrier
	s_waitcnt lgkmcnt(7)
	v_mfma_f32_16x16x32_bf16 v[60:63], v[128:131], v[184:187], v[60:63]
	v_mfma_f32_16x16x32_bf16 v[56:59], v[152:155], v[184:187], v[56:59]
	s_waitcnt lgkmcnt(5)
	v_mfma_f32_16x16x32_bf16 v[44:47], v[128:131], v[192:195], v[44:47]
	v_mfma_f32_16x16x32_bf16 v[40:43], v[152:155], v[192:195], v[40:43]
	s_waitcnt lgkmcnt(3)
	v_mfma_f32_16x16x32_bf16 v[28:31], v[128:131], v[200:203], v[28:31]
	v_mfma_f32_16x16x32_bf16 v[24:27], v[152:155], v[200:203], v[24:27]
	s_waitcnt lgkmcnt(1)
	v_mfma_f32_16x16x32_bf16 v[12:15], v[128:131], v[224:227], v[12:15]
	v_mfma_f32_16x16x32_bf16 v[8:11], v[152:155], v[224:227], v[8:11]
	v_mfma_f32_16x16x32_bf16 v[60:63], v[140:143], v[188:191], v[60:63]
	v_mfma_f32_16x16x32_bf16 v[56:59], v[156:159], v[188:191], v[56:59]
	v_mfma_f32_16x16x32_bf16 v[44:47], v[140:143], v[196:199], v[44:47]
	v_mfma_f32_16x16x32_bf16 v[40:43], v[156:159], v[196:199], v[40:43]
	v_mfma_f32_16x16x32_bf16 v[28:31], v[140:143], v[204:207], v[28:31]
	v_mfma_f32_16x16x32_bf16 v[24:27], v[156:159], v[204:207], v[24:27]
	s_waitcnt lgkmcnt(0)
	v_mfma_f32_16x16x32_bf16 v[12:15], v[140:143], v[228:231], v[12:15]
	v_mfma_f32_16x16x32_bf16 v[8:11], v[156:159], v[228:231], v[8:11]
	v_mfma_f32_16x16x32_bf16 v[52:55], v[168:171], v[184:187], v[52:55]
	v_mfma_f32_16x16x32_bf16 v[48:51], v[176:179], v[184:187], v[48:51]
	v_mfma_f32_16x16x32_bf16 v[36:39], v[168:171], v[192:195], v[36:39]
	v_mfma_f32_16x16x32_bf16 v[32:35], v[176:179], v[192:195], v[32:35]
	v_mfma_f32_16x16x32_bf16 v[20:23], v[168:171], v[200:203], v[20:23]
	v_mfma_f32_16x16x32_bf16 v[16:19], v[176:179], v[200:203], v[16:19]
	v_mfma_f32_16x16x32_bf16 v[4:7], v[168:171], v[224:227], v[4:7]
	v_mfma_f32_16x16x32_bf16 v[0:3], v[176:179], v[224:227], v[0:3]
	v_mfma_f32_16x16x32_bf16 v[52:55], v[172:175], v[188:191], v[52:55]
	v_mfma_f32_16x16x32_bf16 v[48:51], v[180:183], v[188:191], v[48:51]
	v_mfma_f32_16x16x32_bf16 v[36:39], v[172:175], v[196:199], v[36:39]
	v_mfma_f32_16x16x32_bf16 v[32:35], v[180:183], v[196:199], v[32:35]
	v_mfma_f32_16x16x32_bf16 v[20:23], v[172:175], v[204:207], v[20:23]
	v_mfma_f32_16x16x32_bf16 v[16:19], v[180:183], v[204:207], v[16:19]
	v_mfma_f32_16x16x32_bf16 v[4:7], v[172:175], v[228:231], v[4:7]
	v_mfma_f32_16x16x32_bf16 v[0:3], v[180:183], v[228:231], v[0:3]
	s_barrier
	s_add_i32 s10, s10, 2
	s_add_i32 s8, s8, 0x8000
	s_add_i32 s9, s9, 0x8000
	s_cmpk_gt_u32 s10, 0x55
	s_cbranch_scc0 .LBB0_885
